# deferred out-projection tiles (run inside the in-projection phase) use the hand-written LDS-staged epilogue instead of the narrow strided one; they were on the critical path of that phase
# speedup vs baseline: 1.0305x; 1.0093x over previous
; DI int get_tid() { int t = threadIdx.x; asm volatile("" : "+v"(t)); return t; }
; template <bool HN, bool L0>
; DI void phaseC_epi(const Params& p, f32x4 (&acc)[2][2][4][2], int l, int n0, int m0) {
;   const int tid = get_tid(), lane = tid & 63, wid = tid >> 6, wr = wid >> 2, wc = wid & 3, fr = lane & 15, fq = lane >> 4;
;   const bool is_ctx = m0 >= NLAT;
;   const int modrow = is_ctx ? 16 : (m0 / SEQ);
;   const float* xin0 = is_ctx ? p.ctx : p.x;
;   const int rowoff = is_ctx ? NLAT : 0;
;   int tok[4];
; #pragma unroll
;   for (int g = 0; g < 4; ++g) tok[g] = m0 + (g >> 1) * 128 + wc * 32 + (g & 1) * 16 + fr;
;   {
;     const float* gatep = p.mod + (size_t)(l * 17 + modrow) * 3072 + 2048 + n0 + wr * 64 + fq * 4;
;     f32x4 gt[2][4];
; #pragma unroll
;     for (int ai = 0; ai < 2; ++ai)
; #pragma unroll
;       for (int m = 0; m < 4; ++m) gt[ai][m] = *(const f32x4*)(gatep + ai * 128 + m * 16);
; #pragma unroll
;     for (int ai = 0; ai < 2; ++ai)
; #pragma unroll
;       for (int g = 0; g < 4; ++g)
; #pragma unroll
;         for (int m = 0; m < 4; ++m)
; #pragma unroll
;           for (int j = 0; j < 4; ++j) acc[ai][g >> 1][m][g & 1][j] *= gt[ai][m][j];
;   }
;   __builtin_amdgcn_sched_barrier(0);
; #pragma unroll
;   for (int ai = 0; ai < 2; ++ai) {
;     const int f0 = n0 + ai * 128 + wr * 64 + fq * 4;
;     f32x4 gs[4], rgs[4];
; #pragma unroll
;     for (int m = 0; m < 4; ++m) {
;       if (!L0) {
;         const f32x4 g0 = *(const f32x4*)(p.norm_gain + (size_t)l * DM + f0 + m * 16);
;         const f32x4 s0 = *(const f32x4*)(p.mod + (size_t)(l * 17 + modrow) * 3072 + 1024 + f0 + m * 16);
; #pragma unroll
;         for (int j = 0; j < 4; ++j) rgs[m][j] = __builtin_amdgcn_rcpf(g0[j] * (1.f + s0[j]));
;       }
;       if (HN) {
;         const f32x4 g1 = *(const f32x4*)(p.norm_gain + (size_t)(l + 1) * DM + f0 + m * 16);
;         const f32x4 s1 = *(const f32x4*)(p.mod + (size_t)((l + 1) * 17 + modrow) * 3072 + 1024 + f0 + m * 16);
; #pragma unroll
;         for (int j = 0; j < 4; ++j) gs[m][j] = g1[j] * (1.f + s1[j]);
;       }
.LBB0_461:
	s_or_b64 exec, exec, s[2:3]
	s_mov_b32 s8, s26
	s_mov_b64 s[14:15], s[80:81]
	s_barrier
	s_cmp_gt_i32 s8, 2
	s_cbranch_scc1 .Ldf_orig
	s_load_dwordx2 s[4:5], s[14:15], 0x20
	s_load_dwordx2 s[6:7], s[14:15], 0xa0
	s_load_dwordx2 s[10:11], s[14:15], 0xc8
	s_load_dwordx2 s[18:19], s[14:15], 0xe8
	v_bfe_u32 v0, v251, 8, 1
	v_bfe_u32 v230, v251, 4, 2
	v_lshlrev_b32_e32 v227, 4, v230
	v_lshl_or_b32 v227, v0, 8, v227
	v_lshrrev_b32_e32 v231, 5, v251
	v_and_b32_e32 v232, 31, v251
	v_xor_b32_e32 v232, v232, v231
	v_lshlrev_b32_e32 v228, 4, v232
	v_lshl_or_b32 v228, v231, 11, v228
	s_lshr_b32 s0, s29, 3
	s_cmp_gt_i32 s29, 0x7f
	s_cselect_b32 s0, 16, s0
	s_mul_i32 s9, s8, 17
	s_add_i32 s0, s0, s9
	s_mul_i32 s0, s0, 0x3000
	s_lshl_b32 s9, s28, 10
	s_add_u32 s0, s0, s9
	s_lshl_b32 s30, s8, 12
	s_add_u32 s30, s30, s9
	s_lshl_b32 s31, s29, 19
	s_lshl_b32 s9, s28, 9
	s_add_u32 s31, s31, s9
	s_mov_b32 s2, 0xffff
	s_mov_b32 s3, 0
	v_readfirstlane_b32 s9, v251
	s_waitcnt lgkmcnt(0)
	s_add_u32 s10, s10, s0
	s_addc_u32 s11, s11, 0
	s_add_u32 s4, s4, s30
	s_addc_u32 s5, s5, 0
	s_add_u32 s6, s6, s31
	s_addc_u32 s7, s7, 0
	s_lshl_b32 s0, s29, 14
	s_lshl_b32 s30, s28, 4
	s_add_u32 s0, s0, s30
	s_add_u32 s18, s18, s0
	s_addc_u32 s19, s19, 0
	s_lshl_b32 s9, s9, 4
	s_mov_b64 s[12:13], s[6:7]
	s_mov_b32 m0, s9
	s_nop 0
	global_load_lds_dwordx4 v228, s[12:13]
	s_add_u32 s12, s12, 0x8000
	s_addc_u32 s13, s13, 0
	s_add_u32 m0, s9, 0x2000
	s_nop 0
	global_load_lds_dwordx4 v228, s[12:13]
	s_add_u32 s12, s12, 0x8000
	s_addc_u32 s13, s13, 0
	s_add_u32 m0, s9, 0x4000
	s_nop 0
	global_load_lds_dwordx4 v228, s[12:13]
	s_add_u32 s12, s12, 0x8000
	s_addc_u32 s13, s13, 0
	s_add_u32 m0, s9, 0x6000
	s_nop 0
	global_load_lds_dwordx4 v228, s[12:13]
	s_add_u32 s12, s12, 0x8000
	s_addc_u32 s13, s13, 0
	s_add_u32 m0, s9, 0x8000
	s_nop 0
	global_load_lds_dwordx4 v228, s[12:13]
	s_add_u32 s12, s12, 0x8000
	s_addc_u32 s13, s13, 0
	s_add_u32 m0, s9, 0xa000
	s_nop 0
	global_load_lds_dwordx4 v228, s[12:13]
	s_add_u32 s12, s12, 0x8000
	s_addc_u32 s13, s13, 0
	s_add_u32 m0, s9, 0xc000
	s_nop 0
	global_load_lds_dwordx4 v228, s[12:13]
	s_add_u32 s12, s12, 0x8000
	s_addc_u32 s13, s13, 0
	s_add_u32 m0, s9, 0xe000
	s_nop 0
	global_load_lds_dwordx4 v228, s[12:13]
	s_add_u32 s12, s12, 0x8000
	s_addc_u32 s13, s13, 0
	s_add_u32 m0, s9, 0x10000
	s_nop 0
	global_load_lds_dwordx4 v228, s[12:13]
	s_add_u32 s12, s12, 0x8000
	s_addc_u32 s13, s13, 0
	s_add_u32 m0, s9, 0x12000
	s_nop 0
	global_load_lds_dwordx4 v228, s[12:13]
	s_add_u32 s12, s12, 0x8000
	s_addc_u32 s13, s13, 0
	s_add_u32 m0, s9, 0x14000
	s_nop 0
	global_load_lds_dwordx4 v228, s[12:13]
	s_add_u32 s12, s12, 0x8000
	s_addc_u32 s13, s13, 0
	s_add_u32 m0, s9, 0x16000
	s_nop 0
	global_load_lds_dwordx4 v228, s[12:13]
	s_add_u32 s12, s12, 0x8000
	s_addc_u32 s13, s13, 0
	s_add_u32 m0, s9, 0x18000
	s_nop 0
	global_load_lds_dwordx4 v228, s[12:13]
	s_add_u32 s12, s12, 0x8000
	s_addc_u32 s13, s13, 0
	s_add_u32 m0, s9, 0x1a000
	s_nop 0
	global_load_lds_dwordx4 v228, s[12:13]
	s_add_u32 s12, s12, 0x8000
	s_addc_u32 s13, s13, 0
	s_add_u32 m0, s9, 0x1c000
	s_nop 0
	global_load_lds_dwordx4 v228, s[12:13]
	s_add_u32 s12, s12, 0x8000
	s_addc_u32 s13, s13, 0
	s_add_u32 m0, s9, 0x1e000
	s_nop 0
	global_load_lds_dwordx4 v228, s[12:13]
	v_add_u32_e32 v230, 0x2000, v227
	v_add_u32_e32 v231, 0x1000, v227
	v_add_u32_e32 v232, 0x34000, v227
	global_load_dwordx4 v[130:133], v230, s[10:11] offset:0
	global_load_dwordx4 v[134:137], v230, s[10:11] offset:64
	global_load_dwordx4 v[138:141], v230, s[10:11] offset:128
	global_load_dwordx4 v[142:145], v230, s[10:11] offset:192
	global_load_dwordx4 v[146:149], v227, s[4:5] offset:0
	global_load_dwordx4 v[150:153], v227, s[4:5] offset:64
	global_load_dwordx4 v[154:157], v227, s[4:5] offset:128
	global_load_dwordx4 v[158:161], v227, s[4:5] offset:192
	global_load_dwordx4 v[162:165], v231, s[10:11] offset:0
	global_load_dwordx4 v[166:169], v231, s[10:11] offset:64
	global_load_dwordx4 v[170:173], v231, s[10:11] offset:128
	global_load_dwordx4 v[174:177], v231, s[10:11] offset:192
	global_load_dwordx4 v[178:181], v231, s[4:5] offset:0
	global_load_dwordx4 v[182:185], v231, s[4:5] offset:64
	global_load_dwordx4 v[186:189], v231, s[4:5] offset:128
	global_load_dwordx4 v[190:193], v231, s[4:5] offset:192
	global_load_dwordx4 v[194:197], v232, s[10:11] offset:0
	global_load_dwordx4 v[198:201], v232, s[10:11] offset:64
	global_load_dwordx4 v[202:205], v232, s[10:11] offset:128
	global_load_dwordx4 v[206:209], v232, s[10:11] offset:192
	s_waitcnt vmcnt(20)
	s_barrier
; template <bool HN, bool L0>
; DI void phaseC_epi(const Params& p, f32x4 (&acc)[2][2][4][2], int l, int n0, int m0) {
;     ...
;     for (int ai = 0; ai < 2; ++ai)
; #pragma unroll
;       for (int g = 0; g < 4; ++g)
; #pragma unroll
;         for (int m = 0; m < 4; ++m)
; #pragma unroll
;           for (int j = 0; j < 4; ++j) acc[ai][g >> 1][m][g & 1][j] *= gt[ai][m][j];
;   }
;   __builtin_amdgcn_sched_barrier(0);
; #pragma unroll
;   for (int ai = 0; ai < 2; ++ai) {
;     const int f0 = n0 + ai * 128 + wr * 64 + fq * 4;
;     f32x4 gs[4], rgs[4];
; #pragma unroll
;     for (int m = 0; m < 4; ++m) {
;       if (!L0) {
;         const f32x4 g0 = *(const f32x4*)(p.norm_gain + (size_t)l * DM + f0 + m * 16);
;         const f32x4 s0 = *(const f32x4*)(p.mod + (size_t)(l * 17 + modrow) * 3072 + 1024 + f0 + m * 16);
; #pragma unroll
;         for (int j = 0; j < 4; ++j) rgs[m][j] = __builtin_amdgcn_rcpf(g0[j] * (1.f + s0[j]));
;       }
;       if (HN) {
;         const f32x4 g1 = *(const f32x4*)(p.norm_gain + (size_t)(l + 1) * DM + f0 + m * 16);
;         const f32x4 s1 = *(const f32x4*)(p.mod + (size_t)((l + 1) * 17 + modrow) * 3072 + 1024 + f0 + m * 16);
; #pragma unroll
;         for (int j = 0; j < 4; ++j) gs[m][j] = g1[j] * (1.f + s1[j]);
;       }
;     }
; #pragma unroll
;     for (int gp = 0; gp < 2; ++gp) {
;       f32x4 xv[2][4];
;       u32x2 xb[2][4];
; #pragma unroll
;       for (int n = 0; n < 2; ++n)
; #pragma unroll
;         for (int m = 0; m < 4; ++m) {
;           if (L0) xv[n][m] = *(const f32x4*)(xin0 + (size_t)(tok[gp * 2 + n] - rowoff) * DM + f0 + m * 16);
;           else xb[n][m] = *(const u32x2*)(p.xg + (size_t)tok[gp * 2 + n] * DM + f0 + m * 16);
;         }
; #pragma unroll
;       for (int n = 0; n < 2; ++n) {
;         const int g = gp * 2 + n;
;         float ss = 0.f;
; #pragma unroll
;         for (int m = 0; m < 4; ++m) {
;           f32x4 xx;
;           if (L0) xx = xv[n][m];
;           else {
;             xx[0] = hlo(xb[n][m][0]) * rgs[m][0]; xx[1] = hhi(xb[n][m][0]) * rgs[m][1];
;             xx[2] = hlo(xb[n][m][1]) * rgs[m][2]; xx[3] = hhi(xb[n][m][1]) * rgs[m][3];
;           }
;           f32x4 nv;
; #pragma unroll
;           for (int j = 0; j < 4; ++j) { nv[j] = xx[j] + acc[ai][gp][m][n][j]; ss += nv[j] * nv[j]; }
;           if (HN) {
;             u32x2 o;
;             o[0] = pkh2(nv[0] * gs[m][0], nv[1] * gs[m][1]);
	s_waitcnt vmcnt(0)
	v_add_f32_e32 v162, 1.0, v162
	v_add_f32_e32 v163, 1.0, v163
	v_pk_mul_f32 v[146:147], v[146:147], v[162:163]
	v_add_f32_e32 v194, 1.0, v194
	v_add_f32_e32 v195, 1.0, v195
	v_pk_mul_f32 v[178:179], v[178:179], v[194:195]
	v_add_f32_e32 v164, 1.0, v164
	v_add_f32_e32 v165, 1.0, v165
	v_pk_mul_f32 v[148:149], v[148:149], v[164:165]
	v_add_f32_e32 v196, 1.0, v196
	v_add_f32_e32 v197, 1.0, v197
	v_pk_mul_f32 v[180:181], v[180:181], v[196:197]
	v_add_f32_e32 v166, 1.0, v166
	v_add_f32_e32 v167, 1.0, v167
	v_pk_mul_f32 v[150:151], v[150:151], v[166:167]
	v_add_f32_e32 v198, 1.0, v198
	v_add_f32_e32 v199, 1.0, v199
	v_pk_mul_f32 v[182:183], v[182:183], v[198:199]
	v_add_f32_e32 v168, 1.0, v168
	v_add_f32_e32 v169, 1.0, v169
	v_pk_mul_f32 v[152:153], v[152:153], v[168:169]
	v_add_f32_e32 v200, 1.0, v200
	v_add_f32_e32 v201, 1.0, v201
	v_pk_mul_f32 v[184:185], v[184:185], v[200:201]
	v_add_f32_e32 v170, 1.0, v170
	v_add_f32_e32 v171, 1.0, v171
	v_pk_mul_f32 v[154:155], v[154:155], v[170:171]
	v_add_f32_e32 v202, 1.0, v202
	v_add_f32_e32 v203, 1.0, v203
	v_pk_mul_f32 v[186:187], v[186:187], v[202:203]
	v_add_f32_e32 v172, 1.0, v172
	v_add_f32_e32 v173, 1.0, v173
	v_pk_mul_f32 v[156:157], v[156:157], v[172:173]
	v_add_f32_e32 v204, 1.0, v204
	v_add_f32_e32 v205, 1.0, v205
	v_pk_mul_f32 v[188:189], v[188:189], v[204:205]
	v_add_f32_e32 v174, 1.0, v174
	v_add_f32_e32 v175, 1.0, v175
	v_pk_mul_f32 v[158:159], v[158:159], v[174:175]
	v_add_f32_e32 v206, 1.0, v206
	v_add_f32_e32 v207, 1.0, v207
	v_pk_mul_f32 v[190:191], v[190:191], v[206:207]
	v_add_f32_e32 v176, 1.0, v176
	v_add_f32_e32 v177, 1.0, v177
	v_pk_mul_f32 v[160:161], v[160:161], v[176:177]
	v_add_f32_e32 v208, 1.0, v208
	v_add_f32_e32 v209, 1.0, v209
	v_pk_mul_f32 v[192:193], v[192:193], v[208:209]
	v_rcp_f32_e32 v146, v146
	v_rcp_f32_e32 v147, v147
	v_rcp_f32_e32 v148, v148
	v_rcp_f32_e32 v149, v149
	v_rcp_f32_e32 v150, v150
	v_rcp_f32_e32 v151, v151
	v_rcp_f32_e32 v152, v152
	v_rcp_f32_e32 v153, v153
	v_rcp_f32_e32 v154, v154
	v_rcp_f32_e32 v155, v155
	v_rcp_f32_e32 v156, v156
	v_rcp_f32_e32 v157, v157
	v_rcp_f32_e32 v158, v158
	v_rcp_f32_e32 v159, v159
	v_rcp_f32_e32 v160, v160
	v_rcp_f32_e32 v161, v161
	v_pk_mul_f32 v[126:127], v[126:127], v[130:131]
	v_pk_mul_f32 v[128:129], v[128:129], v[132:133]
	v_pk_mul_f32 v[102:103], v[102:103], v[130:131]
	v_pk_mul_f32 v[104:105], v[104:105], v[132:133]
	v_pk_mul_f32 v[122:123], v[122:123], v[134:135]
	v_pk_mul_f32 v[124:125], v[124:125], v[136:137]
	v_pk_mul_f32 v[98:99], v[98:99], v[134:135]
	v_pk_mul_f32 v[100:101], v[100:101], v[136:137]
	v_pk_mul_f32 v[118:119], v[118:119], v[138:139]
	v_pk_mul_f32 v[120:121], v[120:121], v[140:141]
	v_pk_mul_f32 v[106:107], v[106:107], v[138:139]
	v_pk_mul_f32 v[108:109], v[108:109], v[140:141]
	v_pk_mul_f32 v[114:115], v[114:115], v[142:143]
	v_pk_mul_f32 v[116:117], v[116:117], v[144:145]
	v_pk_mul_f32 v[110:111], v[110:111], v[142:143]
	v_pk_mul_f32 v[112:113], v[112:113], v[144:145]
	v_pk_mul_f32 v[82:83], v[82:83], v[130:131]
	v_pk_mul_f32 v[84:85], v[84:85], v[132:133]
	v_pk_mul_f32 v[66:67], v[66:67], v[130:131]
	v_pk_mul_f32 v[68:69], v[68:69], v[132:133]
	v_pk_mul_f32 v[86:87], v[86:87], v[134:135]
	v_pk_mul_f32 v[88:89], v[88:89], v[136:137]
	v_pk_mul_f32 v[74:75], v[74:75], v[134:135]
	v_pk_mul_f32 v[76:77], v[76:77], v[136:137]
	v_pk_mul_f32 v[90:91], v[90:91], v[138:139]
	v_pk_mul_f32 v[92:93], v[92:93], v[140:141]
	v_pk_mul_f32 v[70:71], v[70:71], v[138:139]
	v_pk_mul_f32 v[72:73], v[72:73], v[140:141]
	v_pk_mul_f32 v[94:95], v[94:95], v[142:143]
	v_pk_mul_f32 v[96:97], v[96:97], v[144:145]
	v_pk_mul_f32 v[78:79], v[78:79], v[142:143]
	v_pk_mul_f32 v[80:81], v[80:81], v[144:145]
	v_bfe_u32 v0, v251, 6, 2
	v_and_b32_e32 v231, 15, v251
	v_lshl_or_b32 v0, v0, 5, v231
	v_lshlrev_b32_e32 v0, 9, v0
	v_bfe_u32 v232, v251, 4, 1
	v_lshl_or_b32 v0, v232, 3, v0
	v_bfe_u32 v232, v251, 5, 1
	v_bfe_u32 v233, v251, 8, 1
	v_lshl_or_b32 v232, v233, 3, v232
	v_xor_b32_e32 v232, v232, v231
	v_xor_b32_e32 v233, 0, v232
	v_lshl_or_b32 v166, v233, 4, v0
	v_xor_b32_e32 v233, 2, v232
	v_lshl_or_b32 v167, v233, 4, v0
	v_xor_b32_e32 v233, 4, v232
	v_lshl_or_b32 v168, v233, 4, v0
	v_xor_b32_e32 v233, 6, v232
	v_lshl_or_b32 v169, v233, 4, v0
	v_xor_b32_e32 v162, 16, v240
	v_lshlrev_b32_e32 v162, 2, v162
	v_xor_b32_e32 v163, 32, v240
	v_lshlrev_b32_e32 v163, 2, v163
	v_bfe_u32 v0, v251, 6, 2
	v_and_b32_e32 v164, 15, v251
	v_lshl_or_b32 v164, v0, 5, v164
	v_bfe_u32 v0, v251, 8, 1
	v_lshlrev_b32_e32 v164, 6, v164
	v_lshl_or_b32 v164, v0, 2, v164
	ds_read_b64 v[210:211], v166 offset:0
	ds_read_b64 v[212:213], v167 offset:0
	ds_read_b64 v[214:215], v168 offset:0
	ds_read_b64 v[216:217], v169 offset:0
	ds_read_b64 v[218:219], v166 offset:8192
	ds_read_b64 v[220:221], v167 offset:8192
	ds_read_b64 v[222:223], v168 offset:8192
	ds_read_b64 v[224:225], v169 offset:8192
	s_waitcnt lgkmcnt(7)
	v_cvt_f32_f16_e32 v230, v210
	v_cvt_f32_f16_sdwa v231, v210 dst_sel:DWORD dst_unused:UNUSED_PAD src0_sel:WORD_1
	v_cvt_f32_f16_e32 v232, v211
	v_cvt_f32_f16_sdwa v233, v211 dst_sel:DWORD dst_unused:UNUSED_PAD src0_sel:WORD_1
	v_pk_fma_f32 v[230:231], v[230:231], v[146:147], v[126:127]
	v_pk_fma_f32 v[232:233], v[232:233], v[148:149], v[128:129]
	v_pk_mul_f32 v[170:171], v[230:231], v[230:231]
	v_pk_fma_f32 v[170:171], v[232:233], v[232:233], v[170:171]
	v_pk_mul_f32 v[230:231], v[230:231], v[178:179]
	v_pk_mul_f32 v[232:233], v[232:233], v[180:181]
	v_cvt_pk_f16_f32 v210, v230, v231
	v_cvt_pk_f16_f32 v211, v232, v233
	ds_write_b64 v166, v[210:211] offset:0
	s_waitcnt lgkmcnt(7)
; DI float hlo(unsigned u) { const h2_t v = __builtin_bit_cast(h2_t, u); return (float)v[0]; }
; DI float hhi(unsigned u) { const h2_t v = __builtin_bit_cast(h2_t, u); return (float)v[1]; }
; template <bool HN, bool L0>
; DI void phaseC_epi(const Params& p, f32x4 (&acc)[2][2][4][2], int l, int n0, int m0) {
;     ...
;       for (int n = 0; n < 2; ++n) {
;         const int g = gp * 2 + n;
;         float ss = 0.f;
; #pragma unroll
;         for (int m = 0; m < 4; ++m) {
;           f32x4 xx;
;           if (L0) xx = xv[n][m];
;           else {
;             xx[0] = hlo(xb[n][m][0]) * rgs[m][0]; xx[1] = hhi(xb[n][m][0]) * rgs[m][1];
;             xx[2] = hlo(xb[n][m][1]) * rgs[m][2]; xx[3] = hhi(xb[n][m][1]) * rgs[m][3];
;           }
;           f32x4 nv;
; #pragma unroll
;           for (int j = 0; j < 4; ++j) { nv[j] = xx[j] + acc[ai][gp][m][n][j]; ss += nv[j] * nv[j]; }
;           if (HN) {
;             u32x2 o;
;             o[0] = pkh2(nv[0] * gs[m][0], nv[1] * gs[m][1]);
;             o[1] = pkh2(nv[2] * gs[m][2], nv[3] * gs[m][3]);
;             *(u32x2*)(p.xg + (size_t)tok[g] * DM + f0 + m * 16) = o;
;           } else {
;             *(f32x4*)(p.out + (size_t)tok[g] * DM + f0 + m * 16) = nv;
;           }
;         }
;         if (HN) {
;           ss += __shfl_xor(ss, 16);
;           ss += __shfl_xor(ss, 32);
;           if (fq == 0) p.ssq[(size_t)tok[g] * 16 + (n0 >> 6) + ai * 2 + wr] = ss;
;         }
	v_cvt_f32_f16_e32 v230, v212
	v_cvt_f32_f16_sdwa v231, v212 dst_sel:DWORD dst_unused:UNUSED_PAD src0_sel:WORD_1
	v_cvt_f32_f16_e32 v232, v213
	v_cvt_f32_f16_sdwa v233, v213 dst_sel:DWORD dst_unused:UNUSED_PAD src0_sel:WORD_1
	v_pk_fma_f32 v[230:231], v[230:231], v[150:151], v[122:123]
	v_pk_fma_f32 v[232:233], v[232:233], v[152:153], v[124:125]
	v_pk_fma_f32 v[170:171], v[230:231], v[230:231], v[170:171]
	v_pk_fma_f32 v[170:171], v[232:233], v[232:233], v[170:171]
	v_pk_mul_f32 v[230:231], v[230:231], v[182:183]
	v_pk_mul_f32 v[232:233], v[232:233], v[184:185]
	v_cvt_pk_f16_f32 v212, v230, v231
	v_cvt_pk_f16_f32 v213, v232, v233
	ds_write_b64 v167, v[212:213] offset:0
	s_waitcnt lgkmcnt(7)
	v_cvt_f32_f16_e32 v230, v214
	v_cvt_f32_f16_sdwa v231, v214 dst_sel:DWORD dst_unused:UNUSED_PAD src0_sel:WORD_1
	v_cvt_f32_f16_e32 v232, v215
	v_cvt_f32_f16_sdwa v233, v215 dst_sel:DWORD dst_unused:UNUSED_PAD src0_sel:WORD_1
	v_pk_fma_f32 v[230:231], v[230:231], v[154:155], v[118:119]
	v_pk_fma_f32 v[232:233], v[232:233], v[156:157], v[120:121]
	v_pk_fma_f32 v[170:171], v[230:231], v[230:231], v[170:171]
	v_pk_fma_f32 v[170:171], v[232:233], v[232:233], v[170:171]
	v_pk_mul_f32 v[230:231], v[230:231], v[186:187]
	v_pk_mul_f32 v[232:233], v[232:233], v[188:189]
	v_cvt_pk_f16_f32 v214, v230, v231
	v_cvt_pk_f16_f32 v215, v232, v233
	ds_write_b64 v168, v[214:215] offset:0
	s_waitcnt lgkmcnt(7)
	v_cvt_f32_f16_e32 v230, v216
	v_cvt_f32_f16_sdwa v231, v216 dst_sel:DWORD dst_unused:UNUSED_PAD src0_sel:WORD_1
	v_cvt_f32_f16_e32 v232, v217
	v_cvt_f32_f16_sdwa v233, v217 dst_sel:DWORD dst_unused:UNUSED_PAD src0_sel:WORD_1
	v_pk_fma_f32 v[230:231], v[230:231], v[158:159], v[114:115]
	v_pk_fma_f32 v[232:233], v[232:233], v[160:161], v[116:117]
	v_pk_fma_f32 v[170:171], v[230:231], v[230:231], v[170:171]
	v_pk_fma_f32 v[170:171], v[232:233], v[232:233], v[170:171]
	v_pk_mul_f32 v[230:231], v[230:231], v[190:191]
	v_pk_mul_f32 v[232:233], v[232:233], v[192:193]
	v_cvt_pk_f16_f32 v216, v230, v231
	v_cvt_pk_f16_f32 v217, v232, v233
	ds_write_b64 v169, v[216:217] offset:0
	s_waitcnt lgkmcnt(7)
	v_cvt_f32_f16_e32 v230, v218
	v_cvt_f32_f16_sdwa v231, v218 dst_sel:DWORD dst_unused:UNUSED_PAD src0_sel:WORD_1
	v_cvt_f32_f16_e32 v232, v219
	v_cvt_f32_f16_sdwa v233, v219 dst_sel:DWORD dst_unused:UNUSED_PAD src0_sel:WORD_1
	v_pk_fma_f32 v[230:231], v[230:231], v[146:147], v[102:103]
	v_pk_fma_f32 v[232:233], v[232:233], v[148:149], v[104:105]
	v_pk_mul_f32 v[172:173], v[230:231], v[230:231]
	v_pk_fma_f32 v[172:173], v[232:233], v[232:233], v[172:173]
	v_pk_mul_f32 v[230:231], v[230:231], v[178:179]
	v_pk_mul_f32 v[232:233], v[232:233], v[180:181]
	v_cvt_pk_f16_f32 v218, v230, v231
	v_cvt_pk_f16_f32 v219, v232, v233
	ds_write_b64 v166, v[218:219] offset:8192
	s_waitcnt lgkmcnt(7)
	v_cvt_f32_f16_e32 v230, v220
	v_cvt_f32_f16_sdwa v231, v220 dst_sel:DWORD dst_unused:UNUSED_PAD src0_sel:WORD_1
	v_cvt_f32_f16_e32 v232, v221
	v_cvt_f32_f16_sdwa v233, v221 dst_sel:DWORD dst_unused:UNUSED_PAD src0_sel:WORD_1
	v_pk_fma_f32 v[230:231], v[230:231], v[150:151], v[98:99]
	v_pk_fma_f32 v[232:233], v[232:233], v[152:153], v[100:101]
	v_pk_fma_f32 v[172:173], v[230:231], v[230:231], v[172:173]
	v_pk_fma_f32 v[172:173], v[232:233], v[232:233], v[172:173]
	v_pk_mul_f32 v[230:231], v[230:231], v[182:183]
	v_pk_mul_f32 v[232:233], v[232:233], v[184:185]
	v_cvt_pk_f16_f32 v220, v230, v231
	v_cvt_pk_f16_f32 v221, v232, v233
	ds_write_b64 v167, v[220:221] offset:8192
	s_waitcnt lgkmcnt(7)
	v_cvt_f32_f16_e32 v230, v222
	v_cvt_f32_f16_sdwa v231, v222 dst_sel:DWORD dst_unused:UNUSED_PAD src0_sel:WORD_1
	v_cvt_f32_f16_e32 v232, v223
	v_cvt_f32_f16_sdwa v233, v223 dst_sel:DWORD dst_unused:UNUSED_PAD src0_sel:WORD_1
	v_pk_fma_f32 v[230:231], v[230:231], v[154:155], v[106:107]
	v_pk_fma_f32 v[232:233], v[232:233], v[156:157], v[108:109]
	v_pk_fma_f32 v[172:173], v[230:231], v[230:231], v[172:173]
	v_pk_fma_f32 v[172:173], v[232:233], v[232:233], v[172:173]
	v_pk_mul_f32 v[230:231], v[230:231], v[186:187]
	v_pk_mul_f32 v[232:233], v[232:233], v[188:189]
	v_cvt_pk_f16_f32 v222, v230, v231
	v_cvt_pk_f16_f32 v223, v232, v233
	ds_write_b64 v168, v[222:223] offset:8192
	s_waitcnt lgkmcnt(7)
	v_cvt_f32_f16_e32 v230, v224
	v_cvt_f32_f16_sdwa v231, v224 dst_sel:DWORD dst_unused:UNUSED_PAD src0_sel:WORD_1
	v_cvt_f32_f16_e32 v232, v225
	v_cvt_f32_f16_sdwa v233, v225 dst_sel:DWORD dst_unused:UNUSED_PAD src0_sel:WORD_1
	v_pk_fma_f32 v[230:231], v[230:231], v[158:159], v[110:111]
	v_pk_fma_f32 v[232:233], v[232:233], v[160:161], v[112:113]
	v_pk_fma_f32 v[172:173], v[230:231], v[230:231], v[172:173]
	v_pk_fma_f32 v[172:173], v[232:233], v[232:233], v[172:173]
	v_pk_mul_f32 v[230:231], v[230:231], v[190:191]
	v_pk_mul_f32 v[232:233], v[232:233], v[192:193]
	v_cvt_pk_f16_f32 v224, v230, v231
	v_cvt_pk_f16_f32 v225, v232, v233
	ds_write_b64 v169, v[224:225] offset:8192
	v_add_f32_e32 v170, v170, v171
	v_add_f32_e32 v172, v172, v173
	ds_bpermute_b32 v171, v162, v170
	ds_bpermute_b32 v173, v162, v172
	s_waitcnt lgkmcnt(0)
	v_add_f32_e32 v170, v170, v171
	v_add_f32_e32 v172, v172, v173
	ds_bpermute_b32 v171, v163, v170
	ds_bpermute_b32 v173, v163, v172
	s_waitcnt lgkmcnt(0)
	v_add_f32_e32 v170, v170, v171
	v_add_f32_e32 v172, v172, v173
	s_mov_b64 exec, s[2:3]
	global_store_dword v164, v170, s[18:19] offset:0
	global_store_dword v164, v172, s[18:19] offset:1024
	s_mov_b64 exec, -1
	v_add_u32_e32 v166, 0x10000, v166
	v_add_u32_e32 v167, 0x10000, v167
	v_add_u32_e32 v168, 0x10000, v168
	v_add_u32_e32 v169, 0x10000, v169
	ds_read_b64 v[130:131], v166 offset:0
	ds_read_b64 v[132:133], v167 offset:0
	ds_read_b64 v[134:135], v168 offset:0
	ds_read_b64 v[136:137], v169 offset:0
	ds_read_b64 v[138:139], v166 offset:8192
	ds_read_b64 v[140:141], v167 offset:8192
	ds_read_b64 v[142:143], v168 offset:8192
	ds_read_b64 v[144:145], v169 offset:8192
	s_waitcnt lgkmcnt(7)
; DI float hlo(unsigned u) { const h2_t v = __builtin_bit_cast(h2_t, u); return (float)v[0]; }
; DI float hhi(unsigned u) { const h2_t v = __builtin_bit_cast(h2_t, u); return (float)v[1]; }
; template <bool HN, bool L0>
; DI void phaseC_epi(const Params& p, f32x4 (&acc)[2][2][4][2], int l, int n0, int m0) {
;     ...
;       for (int n = 0; n < 2; ++n) {
;         const int g = gp * 2 + n;
;         float ss = 0.f;
; #pragma unroll
;         for (int m = 0; m < 4; ++m) {
;           f32x4 xx;
;           if (L0) xx = xv[n][m];
;           else {
;             xx[0] = hlo(xb[n][m][0]) * rgs[m][0]; xx[1] = hhi(xb[n][m][0]) * rgs[m][1];
;             xx[2] = hlo(xb[n][m][1]) * rgs[m][2]; xx[3] = hhi(xb[n][m][1]) * rgs[m][3];
;           }
;           f32x4 nv;
; #pragma unroll
;           for (int j = 0; j < 4; ++j) { nv[j] = xx[j] + acc[ai][gp][m][n][j]; ss += nv[j] * nv[j]; }
;           if (HN) {
;             u32x2 o;
;             o[0] = pkh2(nv[0] * gs[m][0], nv[1] * gs[m][1]);
;             o[1] = pkh2(nv[2] * gs[m][2], nv[3] * gs[m][3]);
;             *(u32x2*)(p.xg + (size_t)tok[g] * DM + f0 + m * 16) = o;
;           } else {
;             *(f32x4*)(p.out + (size_t)tok[g] * DM + f0 + m * 16) = nv;
;           }
;         }
;         if (HN) {
;           ss += __shfl_xor(ss, 16);
;           ss += __shfl_xor(ss, 32);
;           if (fq == 0) p.ssq[(size_t)tok[g] * 16 + (n0 >> 6) + ai * 2 + wr] = ss;
;         }
	v_cvt_f32_f16_e32 v230, v130
	v_cvt_f32_f16_sdwa v231, v130 dst_sel:DWORD dst_unused:UNUSED_PAD src0_sel:WORD_1
	v_cvt_f32_f16_e32 v232, v131
	v_cvt_f32_f16_sdwa v233, v131 dst_sel:DWORD dst_unused:UNUSED_PAD src0_sel:WORD_1
	v_pk_fma_f32 v[230:231], v[230:231], v[146:147], v[82:83]
	v_pk_fma_f32 v[232:233], v[232:233], v[148:149], v[84:85]
	v_pk_mul_f32 v[174:175], v[230:231], v[230:231]
	v_pk_fma_f32 v[174:175], v[232:233], v[232:233], v[174:175]
	v_pk_mul_f32 v[230:231], v[230:231], v[178:179]
	v_pk_mul_f32 v[232:233], v[232:233], v[180:181]
	v_cvt_pk_f16_f32 v130, v230, v231
	v_cvt_pk_f16_f32 v131, v232, v233
	ds_write_b64 v166, v[130:131] offset:0
	s_waitcnt lgkmcnt(7)
	v_cvt_f32_f16_e32 v230, v132
	v_cvt_f32_f16_sdwa v231, v132 dst_sel:DWORD dst_unused:UNUSED_PAD src0_sel:WORD_1
	v_cvt_f32_f16_e32 v232, v133
	v_cvt_f32_f16_sdwa v233, v133 dst_sel:DWORD dst_unused:UNUSED_PAD src0_sel:WORD_1
	v_pk_fma_f32 v[230:231], v[230:231], v[150:151], v[86:87]
	v_pk_fma_f32 v[232:233], v[232:233], v[152:153], v[88:89]
	v_pk_fma_f32 v[174:175], v[230:231], v[230:231], v[174:175]
	v_pk_fma_f32 v[174:175], v[232:233], v[232:233], v[174:175]
	v_pk_mul_f32 v[230:231], v[230:231], v[182:183]
	v_pk_mul_f32 v[232:233], v[232:233], v[184:185]
	v_cvt_pk_f16_f32 v132, v230, v231
	v_cvt_pk_f16_f32 v133, v232, v233
	ds_write_b64 v167, v[132:133] offset:0
	s_waitcnt lgkmcnt(7)
	v_cvt_f32_f16_e32 v230, v134
	v_cvt_f32_f16_sdwa v231, v134 dst_sel:DWORD dst_unused:UNUSED_PAD src0_sel:WORD_1
	v_cvt_f32_f16_e32 v232, v135
	v_cvt_f32_f16_sdwa v233, v135 dst_sel:DWORD dst_unused:UNUSED_PAD src0_sel:WORD_1
	v_pk_fma_f32 v[230:231], v[230:231], v[154:155], v[90:91]
	v_pk_fma_f32 v[232:233], v[232:233], v[156:157], v[92:93]
	v_pk_fma_f32 v[174:175], v[230:231], v[230:231], v[174:175]
	v_pk_fma_f32 v[174:175], v[232:233], v[232:233], v[174:175]
	v_pk_mul_f32 v[230:231], v[230:231], v[186:187]
	v_pk_mul_f32 v[232:233], v[232:233], v[188:189]
	v_cvt_pk_f16_f32 v134, v230, v231
	v_cvt_pk_f16_f32 v135, v232, v233
	ds_write_b64 v168, v[134:135] offset:0
	s_waitcnt lgkmcnt(7)
	v_cvt_f32_f16_e32 v230, v136
	v_cvt_f32_f16_sdwa v231, v136 dst_sel:DWORD dst_unused:UNUSED_PAD src0_sel:WORD_1
	v_cvt_f32_f16_e32 v232, v137
	v_cvt_f32_f16_sdwa v233, v137 dst_sel:DWORD dst_unused:UNUSED_PAD src0_sel:WORD_1
	v_pk_fma_f32 v[230:231], v[230:231], v[158:159], v[94:95]
	v_pk_fma_f32 v[232:233], v[232:233], v[160:161], v[96:97]
	v_pk_fma_f32 v[174:175], v[230:231], v[230:231], v[174:175]
	v_pk_fma_f32 v[174:175], v[232:233], v[232:233], v[174:175]
	v_pk_mul_f32 v[230:231], v[230:231], v[190:191]
	v_pk_mul_f32 v[232:233], v[232:233], v[192:193]
	v_cvt_pk_f16_f32 v136, v230, v231
	v_cvt_pk_f16_f32 v137, v232, v233
	ds_write_b64 v169, v[136:137] offset:0
	s_waitcnt lgkmcnt(7)
	v_cvt_f32_f16_e32 v230, v138
	v_cvt_f32_f16_sdwa v231, v138 dst_sel:DWORD dst_unused:UNUSED_PAD src0_sel:WORD_1
	v_cvt_f32_f16_e32 v232, v139
	v_cvt_f32_f16_sdwa v233, v139 dst_sel:DWORD dst_unused:UNUSED_PAD src0_sel:WORD_1
	v_pk_fma_f32 v[230:231], v[230:231], v[146:147], v[66:67]
	v_pk_fma_f32 v[232:233], v[232:233], v[148:149], v[68:69]
	v_pk_mul_f32 v[176:177], v[230:231], v[230:231]
	v_pk_fma_f32 v[176:177], v[232:233], v[232:233], v[176:177]
	v_pk_mul_f32 v[230:231], v[230:231], v[178:179]
	v_pk_mul_f32 v[232:233], v[232:233], v[180:181]
	v_cvt_pk_f16_f32 v138, v230, v231
	v_cvt_pk_f16_f32 v139, v232, v233
	ds_write_b64 v166, v[138:139] offset:8192
	s_waitcnt lgkmcnt(7)
	v_cvt_f32_f16_e32 v230, v140
	v_cvt_f32_f16_sdwa v231, v140 dst_sel:DWORD dst_unused:UNUSED_PAD src0_sel:WORD_1
	v_cvt_f32_f16_e32 v232, v141
	v_cvt_f32_f16_sdwa v233, v141 dst_sel:DWORD dst_unused:UNUSED_PAD src0_sel:WORD_1
	v_pk_fma_f32 v[230:231], v[230:231], v[150:151], v[74:75]
	v_pk_fma_f32 v[232:233], v[232:233], v[152:153], v[76:77]
	v_pk_fma_f32 v[176:177], v[230:231], v[230:231], v[176:177]
	v_pk_fma_f32 v[176:177], v[232:233], v[232:233], v[176:177]
	v_pk_mul_f32 v[230:231], v[230:231], v[182:183]
	v_pk_mul_f32 v[232:233], v[232:233], v[184:185]
	v_cvt_pk_f16_f32 v140, v230, v231
	v_cvt_pk_f16_f32 v141, v232, v233
	ds_write_b64 v167, v[140:141] offset:8192
	s_waitcnt lgkmcnt(7)
	v_cvt_f32_f16_e32 v230, v142
	v_cvt_f32_f16_sdwa v231, v142 dst_sel:DWORD dst_unused:UNUSED_PAD src0_sel:WORD_1
	v_cvt_f32_f16_e32 v232, v143
	v_cvt_f32_f16_sdwa v233, v143 dst_sel:DWORD dst_unused:UNUSED_PAD src0_sel:WORD_1
	v_pk_fma_f32 v[230:231], v[230:231], v[154:155], v[70:71]
	v_pk_fma_f32 v[232:233], v[232:233], v[156:157], v[72:73]
	v_pk_fma_f32 v[176:177], v[230:231], v[230:231], v[176:177]
	v_pk_fma_f32 v[176:177], v[232:233], v[232:233], v[176:177]
	v_pk_mul_f32 v[230:231], v[230:231], v[186:187]
	v_pk_mul_f32 v[232:233], v[232:233], v[188:189]
	v_cvt_pk_f16_f32 v142, v230, v231
	v_cvt_pk_f16_f32 v143, v232, v233
	ds_write_b64 v168, v[142:143] offset:8192
	s_waitcnt lgkmcnt(7)
	v_cvt_f32_f16_e32 v230, v144
	v_cvt_f32_f16_sdwa v231, v144 dst_sel:DWORD dst_unused:UNUSED_PAD src0_sel:WORD_1
	v_cvt_f32_f16_e32 v232, v145
	v_cvt_f32_f16_sdwa v233, v145 dst_sel:DWORD dst_unused:UNUSED_PAD src0_sel:WORD_1
	v_pk_fma_f32 v[230:231], v[230:231], v[158:159], v[78:79]
	v_pk_fma_f32 v[232:233], v[232:233], v[160:161], v[80:81]
	v_pk_fma_f32 v[176:177], v[230:231], v[230:231], v[176:177]
	v_pk_fma_f32 v[176:177], v[232:233], v[232:233], v[176:177]
	v_pk_mul_f32 v[230:231], v[230:231], v[190:191]
	v_pk_mul_f32 v[232:233], v[232:233], v[192:193]
	v_cvt_pk_f16_f32 v144, v230, v231
	v_cvt_pk_f16_f32 v145, v232, v233
	ds_write_b64 v169, v[144:145] offset:8192
	v_add_f32_e32 v174, v174, v175
	v_add_f32_e32 v176, v176, v177
	ds_bpermute_b32 v175, v162, v174
	ds_bpermute_b32 v177, v162, v176
	s_waitcnt lgkmcnt(0)
; template <bool HN, bool L0>
; DI void phaseC_epi(const Params& p, f32x4 (&acc)[2][2][4][2], int l, int n0, int m0) {
;     ...
;     f32x4 gs[4], rgs[4];
; #pragma unroll
;     for (int m = 0; m < 4; ++m) {
;       if (!L0) {
;         const f32x4 g0 = *(const f32x4*)(p.norm_gain + (size_t)l * DM + f0 + m * 16);
;         const f32x4 s0 = *(const f32x4*)(p.mod + (size_t)(l * 17 + modrow) * 3072 + 1024 + f0 + m * 16);
; #pragma unroll
;         for (int j = 0; j < 4; ++j) rgs[m][j] = __builtin_amdgcn_rcpf(g0[j] * (1.f + s0[j]));
;       }
;       if (HN) {
;         const f32x4 g1 = *(const f32x4*)(p.norm_gain + (size_t)(l + 1) * DM + f0 + m * 16);
;         const f32x4 s1 = *(const f32x4*)(p.mod + (size_t)((l + 1) * 17 + modrow) * 3072 + 1024 + f0 + m * 16);
; #pragma unroll
;         for (int j = 0; j < 4; ++j) gs[m][j] = g1[j] * (1.f + s1[j]);
;       }
;     }
; #pragma unroll
;     for (int gp = 0; gp < 2; ++gp) {
;       f32x4 xv[2][4];
;       u32x2 xb[2][4];
; #pragma unroll
;       for (int n = 0; n < 2; ++n)
; #pragma unroll
;         for (int m = 0; m < 4; ++m) {
;           if (L0) xv[n][m] = *(const f32x4*)(xin0 + (size_t)(tok[gp * 2 + n] - rowoff) * DM + f0 + m * 16);
;           else xb[n][m] = *(const u32x2*)(p.xg + (size_t)tok[gp * 2 + n] * DM + f0 + m * 16);
;         }
; #pragma unroll
;       for (int n = 0; n < 2; ++n) {
;         const int g = gp * 2 + n;
;         float ss = 0.f;
; #pragma unroll
;         for (int m = 0; m < 4; ++m) {
;           f32x4 xx;
;           if (L0) xx = xv[n][m];
;           else {
;             xx[0] = hlo(xb[n][m][0]) * rgs[m][0]; xx[1] = hhi(xb[n][m][0]) * rgs[m][1];
;             xx[2] = hlo(xb[n][m][1]) * rgs[m][2]; xx[3] = hhi(xb[n][m][1]) * rgs[m][3];
;           }
;           f32x4 nv;
; #pragma unroll
;           for (int j = 0; j < 4; ++j) { nv[j] = xx[j] + acc[ai][gp][m][n][j]; ss += nv[j] * nv[j]; }
;           if (HN) {
;             u32x2 o;
;             o[0] = pkh2(nv[0] * gs[m][0], nv[1] * gs[m][1]);
;             o[1] = pkh2(nv[2] * gs[m][2], nv[3] * gs[m][3]);
;             *(u32x2*)(p.xg + (size_t)tok[g] * DM + f0 + m * 16) = o;
;           } else {
;             *(f32x4*)(p.out + (size_t)tok[g] * DM + f0 + m * 16) = nv;
;           }
;         }
;         if (HN) {
;           ss += __shfl_xor(ss, 16);
;           ss += __shfl_xor(ss, 32);
	v_add_f32_e32 v174, v174, v175
	v_add_f32_e32 v176, v176, v177
	ds_bpermute_b32 v175, v163, v174
	ds_bpermute_b32 v177, v163, v176
	s_waitcnt lgkmcnt(0)
	v_add_f32_e32 v174, v174, v175
	v_add_f32_e32 v176, v176, v177
	v_add_u32_e32 v229, 0x2000, v164
	s_mov_b64 exec, s[2:3]
	global_store_dword v229, v174, s[18:19] offset:0
	global_store_dword v229, v176, s[18:19] offset:1024
	s_mov_b64 exec, -1
	v_add_u32_e32 v230, 0x2000, v227
	v_add_u32_e32 v231, 0x1000, v227
	v_add_u32_e32 v232, 0x34000, v227
	global_load_dwordx4 v[130:133], v230, s[10:11] offset:512
	global_load_dwordx4 v[134:137], v230, s[10:11] offset:576
	global_load_dwordx4 v[138:141], v230, s[10:11] offset:640
	global_load_dwordx4 v[142:145], v230, s[10:11] offset:704
	global_load_dwordx4 v[146:149], v227, s[4:5] offset:512
	global_load_dwordx4 v[150:153], v227, s[4:5] offset:576
	global_load_dwordx4 v[154:157], v227, s[4:5] offset:640
	global_load_dwordx4 v[158:161], v227, s[4:5] offset:704
	global_load_dwordx4 v[162:165], v231, s[10:11] offset:512
	global_load_dwordx4 v[166:169], v231, s[10:11] offset:576
	global_load_dwordx4 v[170:173], v231, s[10:11] offset:640
	global_load_dwordx4 v[174:177], v231, s[10:11] offset:704
	global_load_dwordx4 v[178:181], v231, s[4:5] offset:512
	global_load_dwordx4 v[182:185], v231, s[4:5] offset:576
	global_load_dwordx4 v[186:189], v231, s[4:5] offset:640
	global_load_dwordx4 v[190:193], v231, s[4:5] offset:704
	global_load_dwordx4 v[194:197], v232, s[10:11] offset:512
	global_load_dwordx4 v[198:201], v232, s[10:11] offset:576
	global_load_dwordx4 v[202:205], v232, s[10:11] offset:640
	global_load_dwordx4 v[206:209], v232, s[10:11] offset:704
	s_waitcnt vmcnt(0)
	v_add_f32_e32 v162, 1.0, v162
	v_add_f32_e32 v163, 1.0, v163
	v_pk_mul_f32 v[146:147], v[146:147], v[162:163]
	v_add_f32_e32 v194, 1.0, v194
	v_add_f32_e32 v195, 1.0, v195
	v_pk_mul_f32 v[178:179], v[178:179], v[194:195]
	v_add_f32_e32 v164, 1.0, v164
	v_add_f32_e32 v165, 1.0, v165
	v_pk_mul_f32 v[148:149], v[148:149], v[164:165]
	v_add_f32_e32 v196, 1.0, v196
	v_add_f32_e32 v197, 1.0, v197
	v_pk_mul_f32 v[180:181], v[180:181], v[196:197]
	v_add_f32_e32 v166, 1.0, v166
	v_add_f32_e32 v167, 1.0, v167
	v_pk_mul_f32 v[150:151], v[150:151], v[166:167]
	v_add_f32_e32 v198, 1.0, v198
	v_add_f32_e32 v199, 1.0, v199
	v_pk_mul_f32 v[182:183], v[182:183], v[198:199]
	v_add_f32_e32 v168, 1.0, v168
	v_add_f32_e32 v169, 1.0, v169
	v_pk_mul_f32 v[152:153], v[152:153], v[168:169]
	v_add_f32_e32 v200, 1.0, v200
	v_add_f32_e32 v201, 1.0, v201
	v_pk_mul_f32 v[184:185], v[184:185], v[200:201]
	v_add_f32_e32 v170, 1.0, v170
	v_add_f32_e32 v171, 1.0, v171
	v_pk_mul_f32 v[154:155], v[154:155], v[170:171]
	v_add_f32_e32 v202, 1.0, v202
	v_add_f32_e32 v203, 1.0, v203
	v_pk_mul_f32 v[186:187], v[186:187], v[202:203]
	v_add_f32_e32 v172, 1.0, v172
	v_add_f32_e32 v173, 1.0, v173
	v_pk_mul_f32 v[156:157], v[156:157], v[172:173]
	v_add_f32_e32 v204, 1.0, v204
	v_add_f32_e32 v205, 1.0, v205
	v_pk_mul_f32 v[188:189], v[188:189], v[204:205]
	v_add_f32_e32 v174, 1.0, v174
	v_add_f32_e32 v175, 1.0, v175
	v_pk_mul_f32 v[158:159], v[158:159], v[174:175]
	v_add_f32_e32 v206, 1.0, v206
	v_add_f32_e32 v207, 1.0, v207
	v_pk_mul_f32 v[190:191], v[190:191], v[206:207]
	v_add_f32_e32 v176, 1.0, v176
	v_add_f32_e32 v177, 1.0, v177
	v_pk_mul_f32 v[160:161], v[160:161], v[176:177]
	v_add_f32_e32 v208, 1.0, v208
	v_add_f32_e32 v209, 1.0, v209
	v_pk_mul_f32 v[192:193], v[192:193], v[208:209]
	v_rcp_f32_e32 v146, v146
	v_rcp_f32_e32 v147, v147
	v_rcp_f32_e32 v148, v148
	v_rcp_f32_e32 v149, v149
	v_rcp_f32_e32 v150, v150
	v_rcp_f32_e32 v151, v151
	v_rcp_f32_e32 v152, v152
	v_rcp_f32_e32 v153, v153
	v_rcp_f32_e32 v154, v154
	v_rcp_f32_e32 v155, v155
	v_rcp_f32_e32 v156, v156
	v_rcp_f32_e32 v157, v157
	v_rcp_f32_e32 v158, v158
	v_rcp_f32_e32 v159, v159
	v_rcp_f32_e32 v160, v160
	v_rcp_f32_e32 v161, v161
	v_pk_mul_f32 v[50:51], v[50:51], v[130:131]
	v_pk_mul_f32 v[52:53], v[52:53], v[132:133]
	v_pk_mul_f32 v[34:35], v[34:35], v[130:131]
	v_pk_mul_f32 v[36:37], v[36:37], v[132:133]
	v_pk_mul_f32 v[54:55], v[54:55], v[134:135]
	v_pk_mul_f32 v[56:57], v[56:57], v[136:137]
	v_pk_mul_f32 v[38:39], v[38:39], v[134:135]
	v_pk_mul_f32 v[40:41], v[40:41], v[136:137]
	v_pk_mul_f32 v[58:59], v[58:59], v[138:139]
	v_pk_mul_f32 v[60:61], v[60:61], v[140:141]
	v_pk_mul_f32 v[42:43], v[42:43], v[138:139]
	v_pk_mul_f32 v[44:45], v[44:45], v[140:141]
	v_pk_mul_f32 v[62:63], v[62:63], v[142:143]
	v_pk_mul_f32 v[64:65], v[64:65], v[144:145]
	v_pk_mul_f32 v[46:47], v[46:47], v[142:143]
	v_pk_mul_f32 v[48:49], v[48:49], v[144:145]
	v_pk_mul_f32 v[18:19], v[18:19], v[130:131]
	v_pk_mul_f32 v[20:21], v[20:21], v[132:133]
	v_pk_mul_f32 v[2:3], v[2:3], v[130:131]
	v_pk_mul_f32 v[4:5], v[4:5], v[132:133]
	v_pk_mul_f32 v[22:23], v[22:23], v[134:135]
	v_pk_mul_f32 v[24:25], v[24:25], v[136:137]
	v_pk_mul_f32 v[10:11], v[10:11], v[134:135]
	v_pk_mul_f32 v[12:13], v[12:13], v[136:137]
	v_pk_mul_f32 v[26:27], v[26:27], v[138:139]
	v_pk_mul_f32 v[28:29], v[28:29], v[140:141]
	v_pk_mul_f32 v[6:7], v[6:7], v[138:139]
	v_pk_mul_f32 v[8:9], v[8:9], v[140:141]
	v_pk_mul_f32 v[30:31], v[30:31], v[142:143]
	v_pk_mul_f32 v[32:33], v[32:33], v[144:145]
	v_pk_mul_f32 v[14:15], v[14:15], v[142:143]
	v_pk_mul_f32 v[16:17], v[16:17], v[144:145]
	v_bfe_u32 v0, v251, 6, 2
	v_and_b32_e32 v231, 15, v251
	v_lshl_or_b32 v0, v0, 5, v231
	v_lshlrev_b32_e32 v0, 9, v0
	v_bfe_u32 v232, v251, 4, 1
	v_lshl_or_b32 v0, v232, 3, v0
	v_bfe_u32 v232, v251, 5, 1
	v_bfe_u32 v233, v251, 8, 1
	v_lshl_or_b32 v232, v233, 3, v232
	v_xor_b32_e32 v232, v232, v231
	v_xor_b32_e32 v233, 0, v232
	v_lshl_or_b32 v166, v233, 4, v0
	v_xor_b32_e32 v233, 2, v232
	v_lshl_or_b32 v167, v233, 4, v0
	v_xor_b32_e32 v233, 4, v232
	v_lshl_or_b32 v168, v233, 4, v0
	v_xor_b32_e32 v233, 6, v232
	v_lshl_or_b32 v169, v233, 4, v0
	v_xor_b32_e32 v162, 16, v240
	v_lshlrev_b32_e32 v162, 2, v162
	v_xor_b32_e32 v163, 32, v240
	v_lshlrev_b32_e32 v163, 2, v163
	v_bfe_u32 v0, v251, 6, 2
	v_and_b32_e32 v164, 15, v251
	v_lshl_or_b32 v164, v0, 5, v164
	v_bfe_u32 v0, v251, 8, 1
	v_lshlrev_b32_e32 v164, 6, v164
	v_lshl_or_b32 v164, v0, 2, v164
	ds_read_b64 v[210:211], v166 offset:256
	ds_read_b64 v[212:213], v167 offset:256
	ds_read_b64 v[214:215], v168 offset:256
	ds_read_b64 v[216:217], v169 offset:256
	ds_read_b64 v[218:219], v166 offset:8448
	ds_read_b64 v[220:221], v167 offset:8448
	ds_read_b64 v[222:223], v168 offset:8448
	ds_read_b64 v[224:225], v169 offset:8448
	s_waitcnt lgkmcnt(7)
; DI float hlo(unsigned u) { const h2_t v = __builtin_bit_cast(h2_t, u); return (float)v[0]; }
; DI float hhi(unsigned u) { const h2_t v = __builtin_bit_cast(h2_t, u); return (float)v[1]; }
; template <bool HN, bool L0>
; DI void phaseC_epi(const Params& p, f32x4 (&acc)[2][2][4][2], int l, int n0, int m0) {
;     ...
;       for (int n = 0; n < 2; ++n) {
;         const int g = gp * 2 + n;
;         float ss = 0.f;
; #pragma unroll
;         for (int m = 0; m < 4; ++m) {
;           f32x4 xx;
;           if (L0) xx = xv[n][m];
;           else {
;             xx[0] = hlo(xb[n][m][0]) * rgs[m][0]; xx[1] = hhi(xb[n][m][0]) * rgs[m][1];
;             xx[2] = hlo(xb[n][m][1]) * rgs[m][2]; xx[3] = hhi(xb[n][m][1]) * rgs[m][3];
;           }
;           f32x4 nv;
; #pragma unroll
;           for (int j = 0; j < 4; ++j) { nv[j] = xx[j] + acc[ai][gp][m][n][j]; ss += nv[j] * nv[j]; }
;           if (HN) {
;             u32x2 o;
;             o[0] = pkh2(nv[0] * gs[m][0], nv[1] * gs[m][1]);
;             o[1] = pkh2(nv[2] * gs[m][2], nv[3] * gs[m][3]);
;             *(u32x2*)(p.xg + (size_t)tok[g] * DM + f0 + m * 16) = o;
;           } else {
;             *(f32x4*)(p.out + (size_t)tok[g] * DM + f0 + m * 16) = nv;
;           }
;         }
	v_cvt_f32_f16_e32 v230, v210
	v_cvt_f32_f16_sdwa v231, v210 dst_sel:DWORD dst_unused:UNUSED_PAD src0_sel:WORD_1
	v_cvt_f32_f16_e32 v232, v211
	v_cvt_f32_f16_sdwa v233, v211 dst_sel:DWORD dst_unused:UNUSED_PAD src0_sel:WORD_1
	v_pk_fma_f32 v[230:231], v[230:231], v[146:147], v[50:51]
	v_pk_fma_f32 v[232:233], v[232:233], v[148:149], v[52:53]
	v_pk_mul_f32 v[170:171], v[230:231], v[230:231]
	v_pk_fma_f32 v[170:171], v[232:233], v[232:233], v[170:171]
	v_pk_mul_f32 v[230:231], v[230:231], v[178:179]
	v_pk_mul_f32 v[232:233], v[232:233], v[180:181]
	v_cvt_pk_f16_f32 v210, v230, v231
	v_cvt_pk_f16_f32 v211, v232, v233
	ds_write_b64 v166, v[210:211] offset:256
	s_waitcnt lgkmcnt(7)
	v_cvt_f32_f16_e32 v230, v212
	v_cvt_f32_f16_sdwa v231, v212 dst_sel:DWORD dst_unused:UNUSED_PAD src0_sel:WORD_1
	v_cvt_f32_f16_e32 v232, v213
	v_cvt_f32_f16_sdwa v233, v213 dst_sel:DWORD dst_unused:UNUSED_PAD src0_sel:WORD_1
	v_pk_fma_f32 v[230:231], v[230:231], v[150:151], v[54:55]
	v_pk_fma_f32 v[232:233], v[232:233], v[152:153], v[56:57]
	v_pk_fma_f32 v[170:171], v[230:231], v[230:231], v[170:171]
	v_pk_fma_f32 v[170:171], v[232:233], v[232:233], v[170:171]
	v_pk_mul_f32 v[230:231], v[230:231], v[182:183]
	v_pk_mul_f32 v[232:233], v[232:233], v[184:185]
	v_cvt_pk_f16_f32 v212, v230, v231
	v_cvt_pk_f16_f32 v213, v232, v233
	ds_write_b64 v167, v[212:213] offset:256
	s_waitcnt lgkmcnt(7)
	v_cvt_f32_f16_e32 v230, v214
	v_cvt_f32_f16_sdwa v231, v214 dst_sel:DWORD dst_unused:UNUSED_PAD src0_sel:WORD_1
	v_cvt_f32_f16_e32 v232, v215
	v_cvt_f32_f16_sdwa v233, v215 dst_sel:DWORD dst_unused:UNUSED_PAD src0_sel:WORD_1
	v_pk_fma_f32 v[230:231], v[230:231], v[154:155], v[58:59]
	v_pk_fma_f32 v[232:233], v[232:233], v[156:157], v[60:61]
	v_pk_fma_f32 v[170:171], v[230:231], v[230:231], v[170:171]
	v_pk_fma_f32 v[170:171], v[232:233], v[232:233], v[170:171]
	v_pk_mul_f32 v[230:231], v[230:231], v[186:187]
	v_pk_mul_f32 v[232:233], v[232:233], v[188:189]
	v_cvt_pk_f16_f32 v214, v230, v231
	v_cvt_pk_f16_f32 v215, v232, v233
	ds_write_b64 v168, v[214:215] offset:256
	s_waitcnt lgkmcnt(7)
	v_cvt_f32_f16_e32 v230, v216
	v_cvt_f32_f16_sdwa v231, v216 dst_sel:DWORD dst_unused:UNUSED_PAD src0_sel:WORD_1
	v_cvt_f32_f16_e32 v232, v217
	v_cvt_f32_f16_sdwa v233, v217 dst_sel:DWORD dst_unused:UNUSED_PAD src0_sel:WORD_1
	v_pk_fma_f32 v[230:231], v[230:231], v[158:159], v[62:63]
	v_pk_fma_f32 v[232:233], v[232:233], v[160:161], v[64:65]
	v_pk_fma_f32 v[170:171], v[230:231], v[230:231], v[170:171]
	v_pk_fma_f32 v[170:171], v[232:233], v[232:233], v[170:171]
	v_pk_mul_f32 v[230:231], v[230:231], v[190:191]
	v_pk_mul_f32 v[232:233], v[232:233], v[192:193]
	v_cvt_pk_f16_f32 v216, v230, v231
	v_cvt_pk_f16_f32 v217, v232, v233
	ds_write_b64 v169, v[216:217] offset:256
	s_waitcnt lgkmcnt(7)
	v_cvt_f32_f16_e32 v230, v218
	v_cvt_f32_f16_sdwa v231, v218 dst_sel:DWORD dst_unused:UNUSED_PAD src0_sel:WORD_1
	v_cvt_f32_f16_e32 v232, v219
	v_cvt_f32_f16_sdwa v233, v219 dst_sel:DWORD dst_unused:UNUSED_PAD src0_sel:WORD_1
	v_pk_fma_f32 v[230:231], v[230:231], v[146:147], v[34:35]
	v_pk_fma_f32 v[232:233], v[232:233], v[148:149], v[36:37]
	v_pk_mul_f32 v[172:173], v[230:231], v[230:231]
	v_pk_fma_f32 v[172:173], v[232:233], v[232:233], v[172:173]
	v_pk_mul_f32 v[230:231], v[230:231], v[178:179]
	v_pk_mul_f32 v[232:233], v[232:233], v[180:181]
	v_cvt_pk_f16_f32 v218, v230, v231
	v_cvt_pk_f16_f32 v219, v232, v233
	ds_write_b64 v166, v[218:219] offset:8448
	s_waitcnt lgkmcnt(7)
	v_cvt_f32_f16_e32 v230, v220
	v_cvt_f32_f16_sdwa v231, v220 dst_sel:DWORD dst_unused:UNUSED_PAD src0_sel:WORD_1
	v_cvt_f32_f16_e32 v232, v221
	v_cvt_f32_f16_sdwa v233, v221 dst_sel:DWORD dst_unused:UNUSED_PAD src0_sel:WORD_1
	v_pk_fma_f32 v[230:231], v[230:231], v[150:151], v[38:39]
	v_pk_fma_f32 v[232:233], v[232:233], v[152:153], v[40:41]
	v_pk_fma_f32 v[172:173], v[230:231], v[230:231], v[172:173]
	v_pk_fma_f32 v[172:173], v[232:233], v[232:233], v[172:173]
	v_pk_mul_f32 v[230:231], v[230:231], v[182:183]
	v_pk_mul_f32 v[232:233], v[232:233], v[184:185]
	v_cvt_pk_f16_f32 v220, v230, v231
	v_cvt_pk_f16_f32 v221, v232, v233
	ds_write_b64 v167, v[220:221] offset:8448
	s_waitcnt lgkmcnt(7)
	v_cvt_f32_f16_e32 v230, v222
	v_cvt_f32_f16_sdwa v231, v222 dst_sel:DWORD dst_unused:UNUSED_PAD src0_sel:WORD_1
	v_cvt_f32_f16_e32 v232, v223
	v_cvt_f32_f16_sdwa v233, v223 dst_sel:DWORD dst_unused:UNUSED_PAD src0_sel:WORD_1
	v_pk_fma_f32 v[230:231], v[230:231], v[154:155], v[42:43]
	v_pk_fma_f32 v[232:233], v[232:233], v[156:157], v[44:45]
	v_pk_fma_f32 v[172:173], v[230:231], v[230:231], v[172:173]
	v_pk_fma_f32 v[172:173], v[232:233], v[232:233], v[172:173]
	v_pk_mul_f32 v[230:231], v[230:231], v[186:187]
	v_pk_mul_f32 v[232:233], v[232:233], v[188:189]
	v_cvt_pk_f16_f32 v222, v230, v231
	v_cvt_pk_f16_f32 v223, v232, v233
	ds_write_b64 v168, v[222:223] offset:8448
	s_waitcnt lgkmcnt(7)
	v_cvt_f32_f16_e32 v230, v224
	v_cvt_f32_f16_sdwa v231, v224 dst_sel:DWORD dst_unused:UNUSED_PAD src0_sel:WORD_1
	v_cvt_f32_f16_e32 v232, v225
	v_cvt_f32_f16_sdwa v233, v225 dst_sel:DWORD dst_unused:UNUSED_PAD src0_sel:WORD_1
	v_pk_fma_f32 v[230:231], v[230:231], v[158:159], v[46:47]
	v_pk_fma_f32 v[232:233], v[232:233], v[160:161], v[48:49]
	v_pk_fma_f32 v[172:173], v[230:231], v[230:231], v[172:173]
	v_pk_fma_f32 v[172:173], v[232:233], v[232:233], v[172:173]
	v_pk_mul_f32 v[230:231], v[230:231], v[190:191]
	v_pk_mul_f32 v[232:233], v[232:233], v[192:193]
	v_cvt_pk_f16_f32 v224, v230, v231
	v_cvt_pk_f16_f32 v225, v232, v233
	ds_write_b64 v169, v[224:225] offset:8448
	v_add_f32_e32 v170, v170, v171
	v_add_f32_e32 v172, v172, v173
	ds_bpermute_b32 v171, v162, v170
	ds_bpermute_b32 v173, v162, v172
	s_waitcnt lgkmcnt(0)
; DI float hlo(unsigned u) { const h2_t v = __builtin_bit_cast(h2_t, u); return (float)v[0]; }
; DI float hhi(unsigned u) { const h2_t v = __builtin_bit_cast(h2_t, u); return (float)v[1]; }
; template <bool HN, bool L0>
; DI void phaseC_epi(const Params& p, f32x4 (&acc)[2][2][4][2], int l, int n0, int m0) {
;     ...
;       for (int n = 0; n < 2; ++n) {
;         const int g = gp * 2 + n;
;         float ss = 0.f;
; #pragma unroll
;         for (int m = 0; m < 4; ++m) {
;           f32x4 xx;
;           if (L0) xx = xv[n][m];
;           else {
;             xx[0] = hlo(xb[n][m][0]) * rgs[m][0]; xx[1] = hhi(xb[n][m][0]) * rgs[m][1];
;             xx[2] = hlo(xb[n][m][1]) * rgs[m][2]; xx[3] = hhi(xb[n][m][1]) * rgs[m][3];
;           }
;           f32x4 nv;
; #pragma unroll
;           for (int j = 0; j < 4; ++j) { nv[j] = xx[j] + acc[ai][gp][m][n][j]; ss += nv[j] * nv[j]; }
;           if (HN) {
;             u32x2 o;
;             o[0] = pkh2(nv[0] * gs[m][0], nv[1] * gs[m][1]);
;             o[1] = pkh2(nv[2] * gs[m][2], nv[3] * gs[m][3]);
;             *(u32x2*)(p.xg + (size_t)tok[g] * DM + f0 + m * 16) = o;
;           } else {
;             *(f32x4*)(p.out + (size_t)tok[g] * DM + f0 + m * 16) = nv;
;           }
;         }
;         if (HN) {
;           ss += __shfl_xor(ss, 16);
;           ss += __shfl_xor(ss, 32);
;           if (fq == 0) p.ssq[(size_t)tok[g] * 16 + (n0 >> 6) + ai * 2 + wr] = ss;
;         }
	v_add_f32_e32 v170, v170, v171
	v_add_f32_e32 v172, v172, v173
	ds_bpermute_b32 v171, v163, v170
	ds_bpermute_b32 v173, v163, v172
	s_waitcnt lgkmcnt(0)
	v_add_f32_e32 v170, v170, v171
	v_add_f32_e32 v172, v172, v173
	s_mov_b64 exec, s[2:3]
	global_store_dword v164, v170, s[18:19] offset:8
	global_store_dword v164, v172, s[18:19] offset:1032
	s_mov_b64 exec, -1
	v_add_u32_e32 v166, 0x10000, v166
	v_add_u32_e32 v167, 0x10000, v167
	v_add_u32_e32 v168, 0x10000, v168
	v_add_u32_e32 v169, 0x10000, v169
	ds_read_b64 v[130:131], v166 offset:256
	ds_read_b64 v[132:133], v167 offset:256
	ds_read_b64 v[134:135], v168 offset:256
	ds_read_b64 v[136:137], v169 offset:256
	ds_read_b64 v[138:139], v166 offset:8448
	ds_read_b64 v[140:141], v167 offset:8448
	ds_read_b64 v[142:143], v168 offset:8448
	ds_read_b64 v[144:145], v169 offset:8448
	s_waitcnt lgkmcnt(7)
	v_cvt_f32_f16_e32 v230, v130
	v_cvt_f32_f16_sdwa v231, v130 dst_sel:DWORD dst_unused:UNUSED_PAD src0_sel:WORD_1
	v_cvt_f32_f16_e32 v232, v131
	v_cvt_f32_f16_sdwa v233, v131 dst_sel:DWORD dst_unused:UNUSED_PAD src0_sel:WORD_1
	v_pk_fma_f32 v[230:231], v[230:231], v[146:147], v[18:19]
	v_pk_fma_f32 v[232:233], v[232:233], v[148:149], v[20:21]
	v_pk_mul_f32 v[174:175], v[230:231], v[230:231]
	v_pk_fma_f32 v[174:175], v[232:233], v[232:233], v[174:175]
	v_pk_mul_f32 v[230:231], v[230:231], v[178:179]
	v_pk_mul_f32 v[232:233], v[232:233], v[180:181]
	v_cvt_pk_f16_f32 v130, v230, v231
	v_cvt_pk_f16_f32 v131, v232, v233
	ds_write_b64 v166, v[130:131] offset:256
	s_waitcnt lgkmcnt(7)
	v_cvt_f32_f16_e32 v230, v132
	v_cvt_f32_f16_sdwa v231, v132 dst_sel:DWORD dst_unused:UNUSED_PAD src0_sel:WORD_1
	v_cvt_f32_f16_e32 v232, v133
	v_cvt_f32_f16_sdwa v233, v133 dst_sel:DWORD dst_unused:UNUSED_PAD src0_sel:WORD_1
	v_pk_fma_f32 v[230:231], v[230:231], v[150:151], v[22:23]
	v_pk_fma_f32 v[232:233], v[232:233], v[152:153], v[24:25]
	v_pk_fma_f32 v[174:175], v[230:231], v[230:231], v[174:175]
	v_pk_fma_f32 v[174:175], v[232:233], v[232:233], v[174:175]
	v_pk_mul_f32 v[230:231], v[230:231], v[182:183]
	v_pk_mul_f32 v[232:233], v[232:233], v[184:185]
	v_cvt_pk_f16_f32 v132, v230, v231
	v_cvt_pk_f16_f32 v133, v232, v233
	ds_write_b64 v167, v[132:133] offset:256
	s_waitcnt lgkmcnt(7)
	v_cvt_f32_f16_e32 v230, v134
	v_cvt_f32_f16_sdwa v231, v134 dst_sel:DWORD dst_unused:UNUSED_PAD src0_sel:WORD_1
	v_cvt_f32_f16_e32 v232, v135
	v_cvt_f32_f16_sdwa v233, v135 dst_sel:DWORD dst_unused:UNUSED_PAD src0_sel:WORD_1
	v_pk_fma_f32 v[230:231], v[230:231], v[154:155], v[26:27]
	v_pk_fma_f32 v[232:233], v[232:233], v[156:157], v[28:29]
	v_pk_fma_f32 v[174:175], v[230:231], v[230:231], v[174:175]
	v_pk_fma_f32 v[174:175], v[232:233], v[232:233], v[174:175]
	v_pk_mul_f32 v[230:231], v[230:231], v[186:187]
	v_pk_mul_f32 v[232:233], v[232:233], v[188:189]
	v_cvt_pk_f16_f32 v134, v230, v231
	v_cvt_pk_f16_f32 v135, v232, v233
	ds_write_b64 v168, v[134:135] offset:256
	s_waitcnt lgkmcnt(7)
	v_cvt_f32_f16_e32 v230, v136
	v_cvt_f32_f16_sdwa v231, v136 dst_sel:DWORD dst_unused:UNUSED_PAD src0_sel:WORD_1
	v_cvt_f32_f16_e32 v232, v137
	v_cvt_f32_f16_sdwa v233, v137 dst_sel:DWORD dst_unused:UNUSED_PAD src0_sel:WORD_1
	v_pk_fma_f32 v[230:231], v[230:231], v[158:159], v[30:31]
	v_pk_fma_f32 v[232:233], v[232:233], v[160:161], v[32:33]
	v_pk_fma_f32 v[174:175], v[230:231], v[230:231], v[174:175]
	v_pk_fma_f32 v[174:175], v[232:233], v[232:233], v[174:175]
	v_pk_mul_f32 v[230:231], v[230:231], v[190:191]
	v_pk_mul_f32 v[232:233], v[232:233], v[192:193]
	v_cvt_pk_f16_f32 v136, v230, v231
	v_cvt_pk_f16_f32 v137, v232, v233
	ds_write_b64 v169, v[136:137] offset:256
	s_waitcnt lgkmcnt(7)
	v_cvt_f32_f16_e32 v230, v138
	v_cvt_f32_f16_sdwa v231, v138 dst_sel:DWORD dst_unused:UNUSED_PAD src0_sel:WORD_1
	v_cvt_f32_f16_e32 v232, v139
	v_cvt_f32_f16_sdwa v233, v139 dst_sel:DWORD dst_unused:UNUSED_PAD src0_sel:WORD_1
	v_pk_fma_f32 v[230:231], v[230:231], v[146:147], v[2:3]
	v_pk_fma_f32 v[232:233], v[232:233], v[148:149], v[4:5]
	v_pk_mul_f32 v[176:177], v[230:231], v[230:231]
	v_pk_fma_f32 v[176:177], v[232:233], v[232:233], v[176:177]
	v_pk_mul_f32 v[230:231], v[230:231], v[178:179]
	v_pk_mul_f32 v[232:233], v[232:233], v[180:181]
	v_cvt_pk_f16_f32 v138, v230, v231
	v_cvt_pk_f16_f32 v139, v232, v233
	ds_write_b64 v166, v[138:139] offset:8448
	s_waitcnt lgkmcnt(7)
	v_cvt_f32_f16_e32 v230, v140
	v_cvt_f32_f16_sdwa v231, v140 dst_sel:DWORD dst_unused:UNUSED_PAD src0_sel:WORD_1
	v_cvt_f32_f16_e32 v232, v141
	v_cvt_f32_f16_sdwa v233, v141 dst_sel:DWORD dst_unused:UNUSED_PAD src0_sel:WORD_1
	v_pk_fma_f32 v[230:231], v[230:231], v[150:151], v[10:11]
	v_pk_fma_f32 v[232:233], v[232:233], v[152:153], v[12:13]
	v_pk_fma_f32 v[176:177], v[230:231], v[230:231], v[176:177]
	v_pk_fma_f32 v[176:177], v[232:233], v[232:233], v[176:177]
	v_pk_mul_f32 v[230:231], v[230:231], v[182:183]
	v_pk_mul_f32 v[232:233], v[232:233], v[184:185]
	v_cvt_pk_f16_f32 v140, v230, v231
	v_cvt_pk_f16_f32 v141, v232, v233
	ds_write_b64 v167, v[140:141] offset:8448
	s_waitcnt lgkmcnt(7)
	v_cvt_f32_f16_e32 v230, v142
	v_cvt_f32_f16_sdwa v231, v142 dst_sel:DWORD dst_unused:UNUSED_PAD src0_sel:WORD_1
	v_cvt_f32_f16_e32 v232, v143
	v_cvt_f32_f16_sdwa v233, v143 dst_sel:DWORD dst_unused:UNUSED_PAD src0_sel:WORD_1
	v_pk_fma_f32 v[230:231], v[230:231], v[154:155], v[6:7]
	v_pk_fma_f32 v[232:233], v[232:233], v[156:157], v[8:9]
	v_pk_fma_f32 v[176:177], v[230:231], v[230:231], v[176:177]
	v_pk_fma_f32 v[176:177], v[232:233], v[232:233], v[176:177]
	v_pk_mul_f32 v[230:231], v[230:231], v[186:187]
	v_pk_mul_f32 v[232:233], v[232:233], v[188:189]
	v_cvt_pk_f16_f32 v142, v230, v231
	v_cvt_pk_f16_f32 v143, v232, v233
	ds_write_b64 v168, v[142:143] offset:8448
	s_waitcnt lgkmcnt(7)
	v_cvt_f32_f16_e32 v230, v144
	v_cvt_f32_f16_sdwa v231, v144 dst_sel:DWORD dst_unused:UNUSED_PAD src0_sel:WORD_1
	v_cvt_f32_f16_e32 v232, v145
	v_cvt_f32_f16_sdwa v233, v145 dst_sel:DWORD dst_unused:UNUSED_PAD src0_sel:WORD_1
	v_pk_fma_f32 v[230:231], v[230:231], v[158:159], v[14:15]
	v_pk_fma_f32 v[232:233], v[232:233], v[160:161], v[16:17]
	v_pk_fma_f32 v[176:177], v[230:231], v[230:231], v[176:177]
	v_pk_fma_f32 v[176:177], v[232:233], v[232:233], v[176:177]
	v_pk_mul_f32 v[230:231], v[230:231], v[190:191]
	v_pk_mul_f32 v[232:233], v[232:233], v[192:193]
	v_cvt_pk_f16_f32 v144, v230, v231
	v_cvt_pk_f16_f32 v145, v232, v233
	ds_write_b64 v169, v[144:145] offset:8448
	v_add_f32_e32 v174, v174, v175
	v_add_f32_e32 v176, v176, v177
	ds_bpermute_b32 v175, v162, v174
	ds_bpermute_b32 v177, v162, v176
	s_waitcnt lgkmcnt(0)
	v_add_f32_e32 v174, v174, v175
	v_add_f32_e32 v176, v176, v177
	ds_bpermute_b32 v175, v163, v174
	ds_bpermute_b32 v177, v163, v176
	s_waitcnt lgkmcnt(0)
	v_add_f32_e32 v174, v174, v175
	v_add_f32_e32 v176, v176, v177
	v_add_u32_e32 v229, 0x2000, v164
	s_mov_b64 exec, s[2:3]
	global_store_dword v229, v174, s[18:19] offset:8
	global_store_dword v229, v176, s[18:19] offset:1032
	s_mov_b64 exec, -1
	s_waitcnt lgkmcnt(0)
	s_barrier
; template <bool HN, bool L0>
; DI void phaseC_epi(const Params& p, f32x4 (&acc)[2][2][4][2], int l, int n0, int m0) {
;     ...
;     const float* gatep = p.mod + (size_t)(l * 17 + modrow) * 3072 + 2048 + n0 + wr * 64 + fq * 4;
;     f32x4 gt[2][4];
; #pragma unroll
;     for (int ai = 0; ai < 2; ++ai)
; #pragma unroll
;       for (int m = 0; m < 4; ++m) gt[ai][m] = *(const f32x4*)(gatep + ai * 128 + m * 16);
; #pragma unroll
;     for (int ai = 0; ai < 2; ++ai)
; #pragma unroll
;       for (int g = 0; g < 4; ++g)
; #pragma unroll
;         for (int m = 0; m < 4; ++m)
; #pragma unroll
;           for (int j = 0; j < 4; ++j) acc[ai][g >> 1][m][g & 1][j] *= gt[ai][m][j];
;   }
;   __builtin_amdgcn_sched_barrier(0);
; #pragma unroll
;   for (int ai = 0; ai < 2; ++ai) {
;     const int f0 = n0 + ai * 128 + wr * 64 + fq * 4;
;     f32x4 gs[4], rgs[4];
; #pragma unroll
;     for (int m = 0; m < 4; ++m) {
;       if (!L0) {
;         const f32x4 g0 = *(const f32x4*)(p.norm_gain + (size_t)l * DM + f0 + m * 16);
;         const f32x4 s0 = *(const f32x4*)(p.mod + (size_t)(l * 17 + modrow) * 3072 + 1024 + f0 + m * 16);
; #pragma unroll
;         for (int j = 0; j < 4; ++j) rgs[m][j] = __builtin_amdgcn_rcpf(g0[j] * (1.f + s0[j]));
;       }
;       if (HN) {
;         const f32x4 g1 = *(const f32x4*)(p.norm_gain + (size_t)(l + 1) * DM + f0 + m * 16);
;         const f32x4 s1 = *(const f32x4*)(p.mod + (size_t)((l + 1) * 17 + modrow) * 3072 + 1024 + f0 + m * 16);
; #pragma unroll
;         for (int j = 0; j < 4; ++j) gs[m][j] = g1[j] * (1.f + s1[j]);
;       }
;     }
; #pragma unroll
;     for (int gp = 0; gp < 2; ++gp) {
;       f32x4 xv[2][4];
;       u32x2 xb[2][4];
; #pragma unroll
;       for (int n = 0; n < 2; ++n)
; #pragma unroll
;         for (int m = 0; m < 4; ++m) {
;           if (L0) xv[n][m] = *(const f32x4*)(xin0 + (size_t)(tok[gp * 2 + n] - rowoff) * DM + f0 + m * 16);
;           else xb[n][m] = *(const u32x2*)(p.xg + (size_t)tok[gp * 2 + n] * DM + f0 + m * 16);
;     ...
;             o[0] = pkh2(nv[0] * gs[m][0], nv[1] * gs[m][1]);
;             o[1] = pkh2(nv[2] * gs[m][2], nv[3] * gs[m][3]);
;             *(u32x2*)(p.xg + (size_t)tok[g] * DM + f0 + m * 16) = o;
	v_lshlrev_b32_e32 v229, 4, v251
	v_add_u32_e32 v0, 0x10000, v229
	ds_read_b128 v[130:133], v229 offset:0
	ds_read_b128 v[134:137], v229 offset:8192
	ds_read_b128 v[138:141], v229 offset:16384
	ds_read_b128 v[142:145], v229 offset:24576
	ds_read_b128 v[146:149], v229 offset:32768
	ds_read_b128 v[150:153], v229 offset:40960
	ds_read_b128 v[154:157], v229 offset:49152
	ds_read_b128 v[158:161], v229 offset:57344
	s_waitcnt lgkmcnt(7)
	global_store_dwordx4 v228, v[130:133], s[6:7]
	s_add_u32 s6, s6, 0x8000
	s_addc_u32 s7, s7, 0
	s_waitcnt lgkmcnt(6)
	global_store_dwordx4 v228, v[134:137], s[6:7]
	s_add_u32 s6, s6, 0x8000
	s_addc_u32 s7, s7, 0
	s_waitcnt lgkmcnt(5)
	global_store_dwordx4 v228, v[138:141], s[6:7]
	s_add_u32 s6, s6, 0x8000
	s_addc_u32 s7, s7, 0
	s_waitcnt lgkmcnt(4)
	global_store_dwordx4 v228, v[142:145], s[6:7]
	s_add_u32 s6, s6, 0x8000
	s_addc_u32 s7, s7, 0
	s_waitcnt lgkmcnt(3)
	global_store_dwordx4 v228, v[146:149], s[6:7]
	s_add_u32 s6, s6, 0x8000
	s_addc_u32 s7, s7, 0
	s_waitcnt lgkmcnt(2)
	global_store_dwordx4 v228, v[150:153], s[6:7]
	s_add_u32 s6, s6, 0x8000
	s_addc_u32 s7, s7, 0
	s_waitcnt lgkmcnt(1)
	global_store_dwordx4 v228, v[154:157], s[6:7]
	s_add_u32 s6, s6, 0x8000
	s_addc_u32 s7, s7, 0
	s_waitcnt lgkmcnt(0)
	global_store_dwordx4 v228, v[158:161], s[6:7]
	s_add_u32 s6, s6, 0x8000
	s_addc_u32 s7, s7, 0
	ds_read_b128 v[130:133], v0 offset:0
	ds_read_b128 v[134:137], v0 offset:8192
	ds_read_b128 v[138:141], v0 offset:16384
	ds_read_b128 v[142:145], v0 offset:24576
	ds_read_b128 v[146:149], v0 offset:32768
	ds_read_b128 v[150:153], v0 offset:40960
	ds_read_b128 v[154:157], v0 offset:49152
	ds_read_b128 v[158:161], v0 offset:57344
	s_waitcnt lgkmcnt(7)
	global_store_dwordx4 v228, v[130:133], s[6:7]
	s_add_u32 s6, s6, 0x8000
	s_addc_u32 s7, s7, 0
	s_waitcnt lgkmcnt(6)
	global_store_dwordx4 v228, v[134:137], s[6:7]
	s_add_u32 s6, s6, 0x8000
	s_addc_u32 s7, s7, 0
	s_waitcnt lgkmcnt(5)
	global_store_dwordx4 v228, v[138:141], s[6:7]
	s_add_u32 s6, s6, 0x8000
	s_addc_u32 s7, s7, 0
	s_waitcnt lgkmcnt(4)
	global_store_dwordx4 v228, v[142:145], s[6:7]
	s_add_u32 s6, s6, 0x8000
	s_addc_u32 s7, s7, 0
	s_waitcnt lgkmcnt(3)
	global_store_dwordx4 v228, v[146:149], s[6:7]
	s_add_u32 s6, s6, 0x8000
	s_addc_u32 s7, s7, 0
	s_waitcnt lgkmcnt(2)
	global_store_dwordx4 v228, v[150:153], s[6:7]
	s_add_u32 s6, s6, 0x8000
	s_addc_u32 s7, s7, 0
	s_waitcnt lgkmcnt(1)
	global_store_dwordx4 v228, v[154:157], s[6:7]
	s_add_u32 s6, s6, 0x8000
	s_addc_u32 s7, s7, 0
	s_waitcnt lgkmcnt(0)
	global_store_dwordx4 v228, v[158:161], s[6:7]
	s_barrier
	s_branch .LBB0_481
.Ldf_orig:
	s_load_dwordx2 s[10:11], s[14:15], 0x20
	s_load_dwordx2 s[6:7], s[14:15], 0xa0
	s_load_dwordx2 s[4:5], s[14:15], 0xc8
	s_cmpk_gt_i32 s29, 0x7f
	s_cselect_b64 s[12:13], -1, 0
	s_cmp_gt_i32 s8, 2
	s_mul_i32 s0, s8, 17
	s_mov_b64 s[2:3], -1
	s_cbranch_scc0 .LBB0_463
	s_ashr_i32 s3, s29, 31
	v_mov_b32_e32 v0, v251
	s_lshr_b32 s3, s3, 29
	s_load_dwordx2 s[16:17], s[14:15], 0x80
	s_add_i32 s3, s29, s3
	v_lshrrev_b32_e32 v131, 1, v0
	s_lshl_b32 s18, s28, 8
	s_lshl_b32 s2, s29, 8
	v_and_b32_e32 v130, 15, v0
	s_ashr_i32 s9, s3, 3
	v_and_b32_e32 v131, 0x60, v131
	v_or3_b32 v162, v130, v131, s2
	s_and_b64 s[2:3], s[12:13], exec
	s_cselect_b32 s2, 16, s9
	s_add_i32 s2, s2, s0
	s_mul_hi_i32 s3, s2, 0x3000
	s_mulk_i32 s2, 0x3000
	s_waitcnt lgkmcnt(0)
	s_add_u32 s30, s4, s2
	s_addc_u32 s31, s5, s3
	s_ashr_i32 s19, s18, 31
	s_lshl_b64 s[2:3], s[18:19], 2
	v_ashrrev_i32_e32 v130, 2, v0
	s_add_u32 s2, s30, s2
	v_and_b32_e32 v164, 0xffffffc0, v130
	v_lshrrev_b32_e32 v0, 2, v0
	s_addc_u32 s3, s31, s3
	v_ashrrev_i32_e32 v165, 31, v164
	v_and_b32_e32 v163, 12, v0
	v_lshl_add_u64 v[130:131], v[164:165], 2, s[2:3]
	v_lshlrev_b32_e32 v0, 2, v163
	v_lshl_add_u64 v[130:131], v[130:131], 0, v[0:1]
	s_mov_b64 s[2:3], 0x2000
	v_lshl_add_u64 v[132:133], v[130:131], 0, s[2:3]
	v_add_co_u32_e32 v130, vcc, s95, v130
	v_or_b32_e32 v182, 16, v162
	s_nop 0
	v_addc_co_u32_e32 v131, vcc, 0, v131, vcc
	global_load_dwordx4 v[158:161], v[130:131], off
	global_load_dwordx4 v[154:157], v[132:133], off offset:64
	global_load_dwordx4 v[150:153], v[132:133], off offset:128
	global_load_dwordx4 v[146:149], v[132:133], off offset:192
	global_load_dwordx4 v[142:145], v[132:133], off offset:512
	global_load_dwordx4 v[138:141], v[132:133], off offset:576
	global_load_dwordx4 v[134:137], v[132:133], off offset:640
	s_nop 0
	global_load_dwordx4 v[130:133], v[132:133], off offset:704
	v_or_b32_e32 v190, 0x80, v162
	v_or_b32_e32 v170, 0x90, v162
	s_mov_b32 s9, s1
	v_add_u32_e32 v0, s18, v164
	s_lshl_b64 s[2:3], s[8:9], 12
	v_or_b32_e32 v166, v0, v163
	s_add_u32 s2, s10, s2
	s_addc_u32 s3, s11, s3
	v_ashrrev_i32_e32 v167, 31, v166
	v_lshlrev_b64 v[188:189], 2, v[166:167]
	s_add_u32 s18, s30, 0x1000
	v_lshl_add_u64 v[164:165], s[2:3], 0, v[188:189]
	s_addc_u32 s19, s31, 0
	v_lshl_add_u64 v[168:169], s[18:19], 0, v[188:189]
	global_load_dwordx4 v[172:175], v[164:165], off
	global_load_dwordx4 v[176:179], v[168:169], off
	v_ashrrev_i32_e32 v163, 31, v162
	v_lshl_add_u64 v[200:201], v[166:167], 1, s[6:7]
	v_ashrrev_i32_e32 v183, 31, v182
	v_ashrrev_i32_e32 v191, 31, v190
	v_ashrrev_i32_e32 v171, 31, v170
	v_add_u32_e32 v166, 0x80, v166
	v_ashrrev_i32_e32 v167, 31, v166
	s_mov_b64 s[2:3], 0
	s_waitcnt vmcnt(0)
	v_add_f32_e32 v0, 1.0, v176
	v_mul_f32_e32 v0, v172, v0
	v_rcp_f32_e32 v192, v0
	v_add_f32_e32 v0, 1.0, v177
	v_mul_f32_e32 v0, v173, v0
	v_rcp_f32_e32 v193, v0
	v_add_f32_e32 v0, 1.0, v178
	v_mul_f32_e32 v0, v174, v0
	v_rcp_f32_e32 v194, v0
	v_add_f32_e32 v0, 1.0, v179
	v_mul_f32_e32 v0, v175, v0
	global_load_dwordx4 v[172:175], v[164:165], off offset:64
	global_load_dwordx4 v[176:179], v[168:169], off offset:64
	v_rcp_f32_e32 v195, v0
	s_waitcnt vmcnt(0)
; DI float hlo(unsigned u) { const h2_t v = __builtin_bit_cast(h2_t, u); return (float)v[0]; }
; DI float hhi(unsigned u) { const h2_t v = __builtin_bit_cast(h2_t, u); return (float)v[1]; }
; template <bool HN, bool L0>
; DI void phaseC_epi(const Params& p, f32x4 (&acc)[2][2][4][2], int l, int n0, int m0) {
;     ...
;       if (!L0) {
;         const f32x4 g0 = *(const f32x4*)(p.norm_gain + (size_t)l * DM + f0 + m * 16);
;         const f32x4 s0 = *(const f32x4*)(p.mod + (size_t)(l * 17 + modrow) * 3072 + 1024 + f0 + m * 16);
; #pragma unroll
;         for (int j = 0; j < 4; ++j) rgs[m][j] = __builtin_amdgcn_rcpf(g0[j] * (1.f + s0[j]));
;       }
;       if (HN) {
;         const f32x4 g1 = *(const f32x4*)(p.norm_gain + (size_t)(l + 1) * DM + f0 + m * 16);
;         const f32x4 s1 = *(const f32x4*)(p.mod + (size_t)((l + 1) * 17 + modrow) * 3072 + 1024 + f0 + m * 16);
; #pragma unroll
;         for (int j = 0; j < 4; ++j) gs[m][j] = g1[j] * (1.f + s1[j]);
;       }
;     }
; #pragma unroll
;     for (int gp = 0; gp < 2; ++gp) {
;       f32x4 xv[2][4];
;       u32x2 xb[2][4];
; #pragma unroll
;       for (int n = 0; n < 2; ++n)
; #pragma unroll
;         for (int m = 0; m < 4; ++m) {
;           if (L0) xv[n][m] = *(const f32x4*)(xin0 + (size_t)(tok[gp * 2 + n] - rowoff) * DM + f0 + m * 16);
;           else xb[n][m] = *(const u32x2*)(p.xg + (size_t)tok[gp * 2 + n] * DM + f0 + m * 16);
;         }
; #pragma unroll
;       for (int n = 0; n < 2; ++n) {
;         const int g = gp * 2 + n;
;         float ss = 0.f;
; #pragma unroll
;         for (int m = 0; m < 4; ++m) {
;           f32x4 xx;
;           if (L0) xx = xv[n][m];
;           else {
;             xx[0] = hlo(xb[n][m][0]) * rgs[m][0]; xx[1] = hhi(xb[n][m][0]) * rgs[m][1];
;             xx[2] = hlo(xb[n][m][1]) * rgs[m][2]; xx[3] = hhi(xb[n][m][1]) * rgs[m][3];
;           }
;           f32x4 nv;
; #pragma unroll
;           for (int j = 0; j < 4; ++j) { nv[j] = xx[j] + acc[ai][gp][m][n][j]; ss += nv[j] * nv[j]; }
;           if (HN) {
;             u32x2 o;
;             o[0] = pkh2(nv[0] * gs[m][0], nv[1] * gs[m][1]);
;             o[1] = pkh2(nv[2] * gs[m][2], nv[3] * gs[m][3]);
;             *(u32x2*)(p.xg + (size_t)tok[g] * DM + f0 + m * 16) = o;
;           } else {
;             *(f32x4*)(p.out + (size_t)tok[g] * DM + f0 + m * 16) = nv;
;           }
	v_add_f32_e32 v0, 1.0, v176
	v_mul_f32_e32 v0, v172, v0
	v_rcp_f32_e32 v184, v0
	v_add_f32_e32 v0, 1.0, v177
	v_mul_f32_e32 v0, v173, v0
	v_rcp_f32_e32 v185, v0
	v_add_f32_e32 v0, 1.0, v178
	v_mul_f32_e32 v0, v174, v0
	v_rcp_f32_e32 v186, v0
	v_add_f32_e32 v0, 1.0, v179
	v_mul_f32_e32 v0, v175, v0
	global_load_dwordx4 v[172:175], v[164:165], off offset:128
	global_load_dwordx4 v[178:181], v[168:169], off offset:128
	v_rcp_f32_e32 v187, v0
	s_waitcnt vmcnt(0)
	v_add_f32_e32 v0, 1.0, v178
	v_mul_f32_e32 v0, v172, v0
	v_rcp_f32_e32 v178, v0
	v_add_f32_e32 v0, 1.0, v179
	v_mul_f32_e32 v0, v173, v0
	v_rcp_f32_e32 v179, v0
	v_add_f32_e32 v0, 1.0, v180
	v_mul_f32_e32 v0, v174, v0
	v_rcp_f32_e32 v180, v0
	v_add_f32_e32 v0, 1.0, v181
	v_mul_f32_e32 v0, v175, v0
	global_load_dwordx4 v[172:175], v[164:165], off offset:192
	global_load_dwordx4 v[196:199], v[168:169], off offset:192
	v_rcp_f32_e32 v181, v0
	v_lshlrev_b64 v[168:169], 11, v[162:163]
	v_lshlrev_b64 v[162:163], 12, v[162:163]
	v_lshl_add_u64 v[162:163], s[16:17], 0, v[162:163]
	v_lshl_add_u64 v[162:163], v[162:163], 0, v[188:189]
	s_waitcnt vmcnt(0)
	v_add_f32_e32 v0, 1.0, v196
	v_mul_f32_e32 v0, v172, v0
	v_rcp_f32_e32 v172, v0
	v_add_f32_e32 v0, 1.0, v197
	v_mul_f32_e32 v0, v173, v0
	v_rcp_f32_e32 v173, v0
	v_add_f32_e32 v0, 1.0, v198
	v_mul_f32_e32 v0, v174, v0
	v_rcp_f32_e32 v176, v0
	v_add_f32_e32 v0, 1.0, v199
	v_mul_f32_e32 v0, v175, v0
	v_lshl_add_u64 v[174:175], v[200:201], 0, v[168:169]
	global_load_dwordx2 v[212:213], v[174:175], off
	global_load_dwordx2 v[208:209], v[174:175], off offset:32
	global_load_dwordx2 v[210:211], v[174:175], off offset:64
	global_load_dwordx2 v[206:207], v[174:175], off offset:96
	v_lshlrev_b64 v[174:175], 11, v[182:183]
	v_lshl_add_u64 v[196:197], v[200:201], 0, v[174:175]
	global_load_dwordx2 v[204:205], v[196:197], off
	global_load_dwordx2 v[202:203], v[196:197], off offset:32
	global_load_dwordx2 v[198:199], v[196:197], off offset:64
	s_nop 0
	global_load_dwordx2 v[196:197], v[196:197], off offset:96
	v_rcp_f32_e32 v177, v0
	v_lshlrev_b64 v[182:183], 12, v[182:183]
	v_lshl_add_u64 v[182:183], s[16:17], 0, v[182:183]
	v_lshl_add_u64 v[182:183], v[182:183], 0, v[188:189]
	s_waitcnt vmcnt(7)
	v_cvt_f32_f16_e32 v214, v212
	v_cvt_f32_f16_sdwa v215, v212 dst_sel:DWORD dst_unused:UNUSED_PAD src0_sel:WORD_1
	v_cvt_f32_f16_e32 v212, v213
	v_cvt_f32_f16_sdwa v213, v213 dst_sel:DWORD dst_unused:UNUSED_PAD src0_sel:WORD_1
	v_pk_mul_f32 v[216:217], v[192:193], v[214:215]
	v_pk_mul_f32 v[212:213], v[194:195], v[212:213]
	s_nop 0
	v_pk_fma_f32 v[214:215], v[128:129], v[160:161], v[212:213]
	v_pk_fma_f32 v[212:213], v[126:127], v[158:159], v[216:217]
	global_store_dwordx4 v[162:163], v[212:215], off
	s_waitcnt vmcnt(7)
	s_nop 0
	v_cvt_f32_f16_e32 v212, v208
	v_cvt_f32_f16_sdwa v213, v208 dst_sel:DWORD dst_unused:UNUSED_PAD src0_sel:WORD_1
	v_cvt_f32_f16_e32 v208, v209
	v_cvt_f32_f16_sdwa v209, v209 dst_sel:DWORD dst_unused:UNUSED_PAD src0_sel:WORD_1
	v_pk_mul_f32 v[212:213], v[184:185], v[212:213]
	s_nop 0
	v_pk_fma_f32 v[212:213], v[122:123], v[154:155], v[212:213]
	v_pk_mul_f32 v[208:209], v[186:187], v[208:209]
	s_nop 0
	v_pk_fma_f32 v[214:215], v[124:125], v[156:157], v[208:209]
	s_waitcnt vmcnt(6)
	v_cvt_f32_f16_e32 v208, v210
	v_cvt_f32_f16_sdwa v209, v210 dst_sel:DWORD dst_unused:UNUSED_PAD src0_sel:WORD_1
	v_cvt_f32_f16_e32 v210, v211
	v_cvt_f32_f16_sdwa v211, v211 dst_sel:DWORD dst_unused:UNUSED_PAD src0_sel:WORD_1
	global_store_dwordx4 v[162:163], v[212:215], off offset:64
	v_pk_mul_f32 v[208:209], v[178:179], v[208:209]
	v_pk_mul_f32 v[210:211], v[180:181], v[210:211]
	s_nop 0
	v_pk_fma_f32 v[210:211], v[120:121], v[152:153], v[210:211]
	v_pk_fma_f32 v[208:209], v[118:119], v[150:151], v[208:209]
	global_store_dwordx4 v[162:163], v[208:211], off offset:128
	s_waitcnt vmcnt(7)
	s_nop 0
	v_cvt_f32_f16_e32 v208, v206
	v_cvt_f32_f16_sdwa v209, v206 dst_sel:DWORD dst_unused:UNUSED_PAD src0_sel:WORD_1
	v_cvt_f32_f16_e32 v206, v207
	v_cvt_f32_f16_sdwa v207, v207 dst_sel:DWORD dst_unused:UNUSED_PAD src0_sel:WORD_1
	v_pk_mul_f32 v[210:211], v[172:173], v[208:209]
	v_pk_mul_f32 v[206:207], v[176:177], v[206:207]
	s_nop 0
	v_pk_fma_f32 v[208:209], v[116:117], v[148:149], v[206:207]
	v_pk_fma_f32 v[206:207], v[114:115], v[146:147], v[210:211]
	global_store_dwordx4 v[162:163], v[206:209], off offset:192
	s_waitcnt vmcnt(7)
	s_nop 0
	v_cvt_f32_f16_e32 v206, v204
	v_cvt_f32_f16_sdwa v207, v204 dst_sel:DWORD dst_unused:UNUSED_PAD src0_sel:WORD_1
	v_cvt_f32_f16_e32 v204, v205
	v_cvt_f32_f16_sdwa v205, v205 dst_sel:DWORD dst_unused:UNUSED_PAD src0_sel:WORD_1
	v_pk_mul_f32 v[208:209], v[192:193], v[206:207]
	v_pk_mul_f32 v[204:205], v[194:195], v[204:205]
	s_nop 0
	v_pk_fma_f32 v[206:207], v[104:105], v[160:161], v[204:205]
	v_pk_fma_f32 v[204:205], v[102:103], v[158:159], v[208:209]
	global_store_dwordx4 v[182:183], v[204:207], off
	s_waitcnt vmcnt(7)
	s_nop 0
	v_cvt_f32_f16_e32 v204, v202
	v_cvt_f32_f16_sdwa v205, v202 dst_sel:DWORD dst_unused:UNUSED_PAD src0_sel:WORD_1
	v_cvt_f32_f16_e32 v202, v203
	v_cvt_f32_f16_sdwa v203, v203 dst_sel:DWORD dst_unused:UNUSED_PAD src0_sel:WORD_1
	v_pk_mul_f32 v[206:207], v[184:185], v[204:205]
	v_pk_mul_f32 v[202:203], v[186:187], v[202:203]
	s_nop 0
	v_pk_fma_f32 v[204:205], v[100:101], v[156:157], v[202:203]
	v_pk_fma_f32 v[202:203], v[98:99], v[154:155], v[206:207]
	global_store_dwordx4 v[182:183], v[202:205], off offset:64
	s_waitcnt vmcnt(7)
; DI float hlo(unsigned u) { const h2_t v = __builtin_bit_cast(h2_t, u); return (float)v[0]; }
; DI float hhi(unsigned u) { const h2_t v = __builtin_bit_cast(h2_t, u); return (float)v[1]; }
; template <bool HN, bool L0>
; DI void phaseC_epi(const Params& p, f32x4 (&acc)[2][2][4][2], int l, int n0, int m0) {
;     ...
; #pragma unroll
;     for (int gp = 0; gp < 2; ++gp) {
;       f32x4 xv[2][4];
;       u32x2 xb[2][4];
; #pragma unroll
;       for (int n = 0; n < 2; ++n)
; #pragma unroll
;         for (int m = 0; m < 4; ++m) {
;           if (L0) xv[n][m] = *(const f32x4*)(xin0 + (size_t)(tok[gp * 2 + n] - rowoff) * DM + f0 + m * 16);
;           else xb[n][m] = *(const u32x2*)(p.xg + (size_t)tok[gp * 2 + n] * DM + f0 + m * 16);
;         }
; #pragma unroll
;       for (int n = 0; n < 2; ++n) {
;         const int g = gp * 2 + n;
;         float ss = 0.f;
; #pragma unroll
;         for (int m = 0; m < 4; ++m) {
;           f32x4 xx;
;           if (L0) xx = xv[n][m];
;           else {
;             xx[0] = hlo(xb[n][m][0]) * rgs[m][0]; xx[1] = hhi(xb[n][m][0]) * rgs[m][1];
;             xx[2] = hlo(xb[n][m][1]) * rgs[m][2]; xx[3] = hhi(xb[n][m][1]) * rgs[m][3];
;           }
;           f32x4 nv;
; #pragma unroll
;           for (int j = 0; j < 4; ++j) { nv[j] = xx[j] + acc[ai][gp][m][n][j]; ss += nv[j] * nv[j]; }
;           if (HN) {
;             u32x2 o;
;             o[0] = pkh2(nv[0] * gs[m][0], nv[1] * gs[m][1]);
;             o[1] = pkh2(nv[2] * gs[m][2], nv[3] * gs[m][3]);
;             *(u32x2*)(p.xg + (size_t)tok[g] * DM + f0 + m * 16) = o;
;           } else {
;             *(f32x4*)(p.out + (size_t)tok[g] * DM + f0 + m * 16) = nv;
;           }
	s_nop 0
	v_cvt_f32_f16_e32 v202, v198
	v_cvt_f32_f16_sdwa v203, v198 dst_sel:DWORD dst_unused:UNUSED_PAD src0_sel:WORD_1
	v_cvt_f32_f16_e32 v198, v199
	v_cvt_f32_f16_sdwa v199, v199 dst_sel:DWORD dst_unused:UNUSED_PAD src0_sel:WORD_1
	v_pk_mul_f32 v[202:203], v[178:179], v[202:203]
	s_nop 0
	v_pk_fma_f32 v[202:203], v[106:107], v[150:151], v[202:203]
	v_pk_mul_f32 v[198:199], v[180:181], v[198:199]
	s_nop 0
	v_pk_fma_f32 v[204:205], v[108:109], v[152:153], v[198:199]
	s_waitcnt vmcnt(6)
	v_cvt_f32_f16_e32 v198, v196
	v_cvt_f32_f16_sdwa v199, v196 dst_sel:DWORD dst_unused:UNUSED_PAD src0_sel:WORD_1
	v_cvt_f32_f16_e32 v196, v197
	v_cvt_f32_f16_sdwa v197, v197 dst_sel:DWORD dst_unused:UNUSED_PAD src0_sel:WORD_1
	global_store_dwordx4 v[182:183], v[202:205], off offset:128
	v_pk_mul_f32 v[196:197], v[176:177], v[196:197]
	s_nop 0
	v_pk_mul_f32 v[202:203], v[172:173], v[198:199]
	v_pk_fma_f32 v[198:199], v[112:113], v[148:149], v[196:197]
	v_pk_fma_f32 v[196:197], v[110:111], v[146:147], v[202:203]
	global_store_dwordx4 v[182:183], v[196:199], off offset:192
	s_nop 1
	v_lshlrev_b64 v[196:197], 11, v[190:191]
	v_lshl_add_u64 v[198:199], v[200:201], 0, v[196:197]
	global_load_dwordx2 v[202:203], v[198:199], off
	global_load_dwordx2 v[206:207], v[198:199], off offset:32
	global_load_dwordx2 v[208:209], v[198:199], off offset:64
	global_load_dwordx2 v[210:211], v[198:199], off offset:96
	v_lshlrev_b64 v[198:199], 11, v[170:171]
	v_lshl_add_u64 v[200:201], v[200:201], 0, v[198:199]
	global_load_dwordx2 v[212:213], v[200:201], off
	global_load_dwordx2 v[214:215], v[200:201], off offset:32
	global_load_dwordx2 v[216:217], v[200:201], off offset:64
	s_nop 0
	global_load_dwordx2 v[200:201], v[200:201], off offset:96
	v_lshlrev_b64 v[190:191], 12, v[190:191]
	v_lshl_add_u64 v[190:191], s[16:17], 0, v[190:191]
	v_lshl_add_u64 v[190:191], v[190:191], 0, v[188:189]
	v_lshlrev_b64 v[170:171], 12, v[170:171]
	s_waitcnt vmcnt(7)
	v_cvt_f32_f16_e32 v204, v202
	v_cvt_f32_f16_sdwa v205, v202 dst_sel:DWORD dst_unused:UNUSED_PAD src0_sel:WORD_1
	v_cvt_f32_f16_e32 v202, v203
	v_cvt_f32_f16_sdwa v203, v203 dst_sel:DWORD dst_unused:UNUSED_PAD src0_sel:WORD_1
	v_pk_mul_f32 v[218:219], v[192:193], v[204:205]
	v_pk_mul_f32 v[202:203], v[194:195], v[202:203]
	s_nop 0
	v_pk_fma_f32 v[204:205], v[84:85], v[160:161], v[202:203]
	v_pk_fma_f32 v[202:203], v[82:83], v[158:159], v[218:219]
	global_store_dwordx4 v[190:191], v[202:205], off
	s_waitcnt vmcnt(7)
	s_nop 0
	v_cvt_f32_f16_e32 v202, v206
	v_cvt_f32_f16_sdwa v203, v206 dst_sel:DWORD dst_unused:UNUSED_PAD src0_sel:WORD_1
	v_cvt_f32_f16_e32 v204, v207
	v_cvt_f32_f16_sdwa v205, v207 dst_sel:DWORD dst_unused:UNUSED_PAD src0_sel:WORD_1
	v_pk_mul_f32 v[202:203], v[184:185], v[202:203]
	s_nop 0
	v_pk_fma_f32 v[202:203], v[86:87], v[154:155], v[202:203]
	v_pk_mul_f32 v[204:205], v[186:187], v[204:205]
	s_nop 0
	v_pk_fma_f32 v[204:205], v[88:89], v[156:157], v[204:205]
	global_store_dwordx4 v[190:191], v[202:205], off offset:64
	s_waitcnt vmcnt(7)
	s_nop 0
	v_cvt_f32_f16_e32 v202, v208
	v_cvt_f32_f16_sdwa v203, v208 dst_sel:DWORD dst_unused:UNUSED_PAD src0_sel:WORD_1
	v_cvt_f32_f16_e32 v204, v209
	v_cvt_f32_f16_sdwa v205, v209 dst_sel:DWORD dst_unused:UNUSED_PAD src0_sel:WORD_1
	v_pk_mul_f32 v[202:203], v[178:179], v[202:203]
	s_nop 0
	v_pk_fma_f32 v[202:203], v[90:91], v[150:151], v[202:203]
	v_pk_mul_f32 v[204:205], v[180:181], v[204:205]
	s_nop 0
	v_pk_fma_f32 v[204:205], v[92:93], v[152:153], v[204:205]
	global_store_dwordx4 v[190:191], v[202:205], off offset:128
	s_waitcnt vmcnt(7)
	s_nop 0
	v_cvt_f32_f16_e32 v202, v210
	v_cvt_f32_f16_sdwa v203, v210 dst_sel:DWORD dst_unused:UNUSED_PAD src0_sel:WORD_1
	v_cvt_f32_f16_e32 v204, v211
	v_cvt_f32_f16_sdwa v205, v211 dst_sel:DWORD dst_unused:UNUSED_PAD src0_sel:WORD_1
	v_pk_mul_f32 v[202:203], v[172:173], v[202:203]
	s_nop 0
	v_pk_fma_f32 v[202:203], v[94:95], v[146:147], v[202:203]
	v_pk_mul_f32 v[204:205], v[176:177], v[204:205]
	s_nop 0
	v_pk_fma_f32 v[204:205], v[96:97], v[148:149], v[204:205]
	global_store_dwordx4 v[190:191], v[202:205], off offset:192
	s_waitcnt vmcnt(7)
	s_nop 0
	v_cvt_f32_f16_e32 v202, v212
	v_cvt_f32_f16_sdwa v203, v212 dst_sel:DWORD dst_unused:UNUSED_PAD src0_sel:WORD_1
	v_cvt_f32_f16_e32 v204, v213
	v_cvt_f32_f16_sdwa v205, v213 dst_sel:DWORD dst_unused:UNUSED_PAD src0_sel:WORD_1
	v_pk_mul_f32 v[192:193], v[192:193], v[202:203]
	s_nop 0
	v_pk_fma_f32 v[192:193], v[66:67], v[158:159], v[192:193]
	v_pk_mul_f32 v[194:195], v[194:195], v[204:205]
	v_lshl_add_u64 v[158:159], s[16:17], 0, v[170:171]
	v_pk_fma_f32 v[194:195], v[68:69], v[160:161], v[194:195]
	s_waitcnt vmcnt(6)
	v_cvt_f32_f16_e32 v160, v214
	v_cvt_f32_f16_sdwa v161, v214 dst_sel:DWORD dst_unused:UNUSED_PAD src0_sel:WORD_1
	v_cvt_f32_f16_e32 v170, v215
	v_cvt_f32_f16_sdwa v171, v215 dst_sel:DWORD dst_unused:UNUSED_PAD src0_sel:WORD_1
	v_lshl_add_u64 v[158:159], v[158:159], 0, v[188:189]
	v_pk_mul_f32 v[160:161], v[184:185], v[160:161]
	global_store_dwordx4 v[158:159], v[192:195], off
	v_pk_mul_f32 v[170:171], v[186:187], v[170:171]
	v_pk_fma_f32 v[154:155], v[74:75], v[154:155], v[160:161]
	v_pk_fma_f32 v[156:157], v[76:77], v[156:157], v[170:171]
	global_store_dwordx4 v[158:159], v[154:157], off offset:64
	v_lshl_add_u64 v[160:161], v[166:167], 2, s[18:19]
	v_lshl_add_u64 v[166:167], v[166:167], 1, s[6:7]
	s_waitcnt vmcnt(7)
; template <bool HN, bool L0>
; DI void phaseC_epi(const Params& p, f32x4 (&acc)[2][2][4][2], int l, int n0, int m0) {
;     ...
;   for (int ai = 0; ai < 2; ++ai) {
;     const int f0 = n0 + ai * 128 + wr * 64 + fq * 4;
;     f32x4 gs[4], rgs[4];
; #pragma unroll
;     for (int m = 0; m < 4; ++m) {
;       if (!L0) {
;         const f32x4 g0 = *(const f32x4*)(p.norm_gain + (size_t)l * DM + f0 + m * 16);
;         const f32x4 s0 = *(const f32x4*)(p.mod + (size_t)(l * 17 + modrow) * 3072 + 1024 + f0 + m * 16);
; #pragma unroll
;         for (int j = 0; j < 4; ++j) rgs[m][j] = __builtin_amdgcn_rcpf(g0[j] * (1.f + s0[j]));
;       }
;       if (HN) {
;         const f32x4 g1 = *(const f32x4*)(p.norm_gain + (size_t)(l + 1) * DM + f0 + m * 16);
;         const f32x4 s1 = *(const f32x4*)(p.mod + (size_t)((l + 1) * 17 + modrow) * 3072 + 1024 + f0 + m * 16);
; #pragma unroll
;         for (int j = 0; j < 4; ++j) gs[m][j] = g1[j] * (1.f + s1[j]);
;       }
;     }
; #pragma unroll
;     for (int gp = 0; gp < 2; ++gp) {
;       f32x4 xv[2][4];
;       u32x2 xb[2][4];
; #pragma unroll
;       for (int n = 0; n < 2; ++n)
; #pragma unroll
;         for (int m = 0; m < 4; ++m) {
;           if (L0) xv[n][m] = *(const f32x4*)(xin0 + (size_t)(tok[gp * 2 + n] - rowoff) * DM + f0 + m * 16);
;           else xb[n][m] = *(const u32x2*)(p.xg + (size_t)tok[gp * 2 + n] * DM + f0 + m * 16);
;         }
; #pragma unroll
;       for (int n = 0; n < 2; ++n) {
;         const int g = gp * 2 + n;
;         float ss = 0.f;
; #pragma unroll
;         for (int m = 0; m < 4; ++m) {
;           f32x4 xx;
;           if (L0) xx = xv[n][m];
;           else {
;             xx[0] = hlo(xb[n][m][0]) * rgs[m][0]; xx[1] = hhi(xb[n][m][0]) * rgs[m][1];
;             xx[2] = hlo(xb[n][m][1]) * rgs[m][2]; xx[3] = hhi(xb[n][m][1]) * rgs[m][3];
;           }
;           f32x4 nv;
; #pragma unroll
;           for (int j = 0; j < 4; ++j) { nv[j] = xx[j] + acc[ai][gp][m][n][j]; ss += nv[j] * nv[j]; }
;           if (HN) {
;             u32x2 o;
;             o[0] = pkh2(nv[0] * gs[m][0], nv[1] * gs[m][1]);
;             o[1] = pkh2(nv[2] * gs[m][2], nv[3] * gs[m][3]);
;             *(u32x2*)(p.xg + (size_t)tok[g] * DM + f0 + m * 16) = o;
;           } else {
;             *(f32x4*)(p.out + (size_t)tok[g] * DM + f0 + m * 16) = nv;
;           }
	v_cvt_f32_f16_e32 v154, v216
	v_cvt_f32_f16_sdwa v155, v216 dst_sel:DWORD dst_unused:UNUSED_PAD src0_sel:WORD_1
	v_cvt_f32_f16_e32 v156, v217
	v_cvt_f32_f16_sdwa v157, v217 dst_sel:DWORD dst_unused:UNUSED_PAD src0_sel:WORD_1
	v_lshl_add_u64 v[168:169], v[166:167], 0, v[168:169]
	v_pk_mul_f32 v[154:155], v[178:179], v[154:155]
	v_pk_mul_f32 v[156:157], v[180:181], v[156:157]
	s_nop 0
	v_pk_fma_f32 v[152:153], v[72:73], v[152:153], v[156:157]
	v_pk_fma_f32 v[150:151], v[70:71], v[150:151], v[154:155]
	global_store_dwordx4 v[158:159], v[150:153], off offset:128
	s_waitcnt vmcnt(7)
	s_nop 0
	v_cvt_f32_f16_e32 v150, v200
	v_cvt_f32_f16_sdwa v151, v200 dst_sel:DWORD dst_unused:UNUSED_PAD src0_sel:WORD_1
	v_cvt_f32_f16_e32 v152, v201
	v_cvt_f32_f16_sdwa v153, v201 dst_sel:DWORD dst_unused:UNUSED_PAD src0_sel:WORD_1
	v_pk_mul_f32 v[150:151], v[172:173], v[150:151]
	s_nop 0
	v_pk_fma_f32 v[146:147], v[78:79], v[146:147], v[150:151]
	v_pk_mul_f32 v[152:153], v[176:177], v[152:153]
	s_nop 0
	v_pk_fma_f32 v[148:149], v[80:81], v[148:149], v[152:153]
	global_store_dwordx4 v[158:159], v[146:149], off offset:192
	global_load_dwordx4 v[146:149], v[164:165], off offset:512
	s_nop 0
	global_load_dwordx4 v[150:153], v[160:161], off
	s_waitcnt vmcnt(0)
	v_add_f32_e32 v0, 1.0, v150
	v_mul_f32_e32 v0, v146, v0
	v_rcp_f32_e32 v146, v0
	v_add_f32_e32 v0, 1.0, v151
	v_mul_f32_e32 v0, v147, v0
	v_rcp_f32_e32 v147, v0
	v_add_f32_e32 v0, 1.0, v152
	v_mul_f32_e32 v0, v148, v0
	v_rcp_f32_e32 v148, v0
	v_add_f32_e32 v0, 1.0, v153
	global_load_dwordx4 v[150:153], v[164:165], off offset:576
	global_load_dwordx4 v[154:157], v[160:161], off offset:64
	v_mul_f32_e32 v0, v149, v0
	v_rcp_f32_e32 v149, v0
	s_waitcnt vmcnt(0)
	v_add_f32_e32 v0, 1.0, v154
	v_mul_f32_e32 v0, v150, v0
	v_rcp_f32_e32 v150, v0
	v_add_f32_e32 v0, 1.0, v155
	v_mul_f32_e32 v0, v151, v0
	v_rcp_f32_e32 v151, v0
	v_add_f32_e32 v0, 1.0, v156
	v_mul_f32_e32 v0, v152, v0
	v_rcp_f32_e32 v152, v0
	v_add_f32_e32 v0, 1.0, v157
	global_load_dwordx4 v[154:157], v[164:165], off offset:640
	global_load_dwordx4 v[170:173], v[160:161], off offset:128
	v_mul_f32_e32 v0, v153, v0
	v_rcp_f32_e32 v153, v0
	s_waitcnt vmcnt(0)
	v_add_f32_e32 v0, 1.0, v170
	v_mul_f32_e32 v0, v154, v0
	v_rcp_f32_e32 v154, v0
	v_add_f32_e32 v0, 1.0, v171
	v_mul_f32_e32 v0, v155, v0
	v_rcp_f32_e32 v155, v0
	v_add_f32_e32 v0, 1.0, v172
	v_mul_f32_e32 v0, v156, v0
	v_rcp_f32_e32 v156, v0
	v_add_f32_e32 v0, 1.0, v173
	global_load_dwordx4 v[170:173], v[164:165], off offset:704
	global_load_dwordx4 v[176:179], v[160:161], off offset:192
	v_mul_f32_e32 v0, v157, v0
	v_rcp_f32_e32 v157, v0
	s_waitcnt vmcnt(0)
	v_add_f32_e32 v0, 1.0, v176
	v_mul_f32_e32 v0, v170, v0
	v_rcp_f32_e32 v160, v0
	v_add_f32_e32 v0, 1.0, v177
	v_mul_f32_e32 v0, v171, v0
	v_rcp_f32_e32 v161, v0
	v_add_f32_e32 v0, 1.0, v178
	v_mul_f32_e32 v0, v172, v0
	v_rcp_f32_e32 v164, v0
	v_add_f32_e32 v0, 1.0, v179
	global_load_dwordx2 v[180:181], v[168:169], off
	global_load_dwordx2 v[188:189], v[168:169], off offset:32
	global_load_dwordx2 v[178:179], v[168:169], off offset:64
	global_load_dwordx2 v[176:177], v[168:169], off offset:96
	v_lshl_add_u64 v[168:169], v[166:167], 0, v[174:175]
	v_mul_f32_e32 v0, v173, v0
	global_load_dwordx2 v[174:175], v[168:169], off
	global_load_dwordx2 v[172:173], v[168:169], off offset:32
	global_load_dwordx2 v[170:171], v[168:169], off offset:64
	s_nop 0
	global_load_dwordx2 v[168:169], v[168:169], off offset:96
	v_rcp_f32_e32 v165, v0
	s_waitcnt vmcnt(7)
	v_cvt_f32_f16_e32 v184, v180
	v_cvt_f32_f16_sdwa v185, v180 dst_sel:DWORD dst_unused:UNUSED_PAD src0_sel:WORD_1
	v_cvt_f32_f16_e32 v180, v181
	v_cvt_f32_f16_sdwa v181, v181 dst_sel:DWORD dst_unused:UNUSED_PAD src0_sel:WORD_1
	v_pk_mul_f32 v[184:185], v[146:147], v[184:185]
	s_nop 0
	v_pk_fma_f32 v[184:185], v[50:51], v[142:143], v[184:185]
	v_pk_mul_f32 v[180:181], v[148:149], v[180:181]
	s_nop 0
	v_pk_fma_f32 v[186:187], v[52:53], v[144:145], v[180:181]
	global_store_dwordx4 v[162:163], v[184:187], off offset:512
	s_waitcnt vmcnt(7)
	v_cvt_f32_f16_e32 v180, v188
	v_cvt_f32_f16_sdwa v181, v188 dst_sel:DWORD dst_unused:UNUSED_PAD src0_sel:WORD_1
	v_cvt_f32_f16_e32 v184, v189
	v_cvt_f32_f16_sdwa v185, v189 dst_sel:DWORD dst_unused:UNUSED_PAD src0_sel:WORD_1
	v_pk_mul_f32 v[180:181], v[150:151], v[180:181]
	v_pk_mul_f32 v[184:185], v[152:153], v[184:185]
	s_nop 0
	v_pk_fma_f32 v[186:187], v[56:57], v[140:141], v[184:185]
	v_pk_fma_f32 v[184:185], v[54:55], v[138:139], v[180:181]
	s_waitcnt vmcnt(6)
	v_cvt_f32_f16_e32 v180, v178
	v_cvt_f32_f16_sdwa v181, v178 dst_sel:DWORD dst_unused:UNUSED_PAD src0_sel:WORD_1
	v_cvt_f32_f16_e32 v178, v179
	v_cvt_f32_f16_sdwa v179, v179 dst_sel:DWORD dst_unused:UNUSED_PAD src0_sel:WORD_1
	global_store_dwordx4 v[162:163], v[184:187], off offset:576
	v_pk_mul_f32 v[178:179], v[156:157], v[178:179]
	s_nop 0
	v_pk_mul_f32 v[184:185], v[154:155], v[180:181]
	v_pk_fma_f32 v[180:181], v[60:61], v[136:137], v[178:179]
	v_pk_fma_f32 v[178:179], v[58:59], v[134:135], v[184:185]
	global_store_dwordx4 v[162:163], v[178:181], off offset:640
	s_waitcnt vmcnt(7)
	s_nop 0
	v_cvt_f32_f16_e32 v178, v176
	v_cvt_f32_f16_sdwa v179, v176 dst_sel:DWORD dst_unused:UNUSED_PAD src0_sel:WORD_1
	v_cvt_f32_f16_e32 v176, v177
	v_cvt_f32_f16_sdwa v177, v177 dst_sel:DWORD dst_unused:UNUSED_PAD src0_sel:WORD_1
	v_pk_mul_f32 v[180:181], v[160:161], v[178:179]
	v_pk_mul_f32 v[176:177], v[164:165], v[176:177]
	s_nop 0
	v_pk_fma_f32 v[178:179], v[64:65], v[132:133], v[176:177]
	v_pk_fma_f32 v[176:177], v[62:63], v[130:131], v[180:181]
	global_store_dwordx4 v[162:163], v[176:179], off offset:704
	s_waitcnt vmcnt(7)
; DI float hlo(unsigned u) { const h2_t v = __builtin_bit_cast(h2_t, u); return (float)v[0]; }
; DI float hhi(unsigned u) { const h2_t v = __builtin_bit_cast(h2_t, u); return (float)v[1]; }
; template <bool HN, bool L0>
; DI void phaseC_epi(const Params& p, f32x4 (&acc)[2][2][4][2], int l, int n0, int m0) {
;     ...
;       for (int n = 0; n < 2; ++n)
; #pragma unroll
;         for (int m = 0; m < 4; ++m) {
;           if (L0) xv[n][m] = *(const f32x4*)(xin0 + (size_t)(tok[gp * 2 + n] - rowoff) * DM + f0 + m * 16);
;           else xb[n][m] = *(const u32x2*)(p.xg + (size_t)tok[gp * 2 + n] * DM + f0 + m * 16);
;         }
; #pragma unroll
;       for (int n = 0; n < 2; ++n) {
;         const int g = gp * 2 + n;
;         float ss = 0.f;
; #pragma unroll
;         for (int m = 0; m < 4; ++m) {
;           f32x4 xx;
;           if (L0) xx = xv[n][m];
;           else {
;             xx[0] = hlo(xb[n][m][0]) * rgs[m][0]; xx[1] = hhi(xb[n][m][0]) * rgs[m][1];
;             xx[2] = hlo(xb[n][m][1]) * rgs[m][2]; xx[3] = hhi(xb[n][m][1]) * rgs[m][3];
;           }
;           f32x4 nv;
; #pragma unroll
;           for (int j = 0; j < 4; ++j) { nv[j] = xx[j] + acc[ai][gp][m][n][j]; ss += nv[j] * nv[j]; }
;           if (HN) {
;             u32x2 o;
;             o[0] = pkh2(nv[0] * gs[m][0], nv[1] * gs[m][1]);
;             o[1] = pkh2(nv[2] * gs[m][2], nv[3] * gs[m][3]);
;             *(u32x2*)(p.xg + (size_t)tok[g] * DM + f0 + m * 16) = o;
;           } else {
;             *(f32x4*)(p.out + (size_t)tok[g] * DM + f0 + m * 16) = nv;
;           }
	v_cvt_f32_f16_e32 v162, v174
	v_cvt_f32_f16_sdwa v163, v174 dst_sel:DWORD dst_unused:UNUSED_PAD src0_sel:WORD_1
	v_cvt_f32_f16_e32 v174, v175
	v_cvt_f32_f16_sdwa v175, v175 dst_sel:DWORD dst_unused:UNUSED_PAD src0_sel:WORD_1
	v_pk_mul_f32 v[162:163], v[146:147], v[162:163]
	v_pk_mul_f32 v[174:175], v[148:149], v[174:175]
	s_nop 0
	v_pk_fma_f32 v[176:177], v[36:37], v[144:145], v[174:175]
	v_pk_fma_f32 v[174:175], v[34:35], v[142:143], v[162:163]
	s_waitcnt vmcnt(6)
	v_cvt_f32_f16_e32 v162, v172
	v_cvt_f32_f16_sdwa v163, v172 dst_sel:DWORD dst_unused:UNUSED_PAD src0_sel:WORD_1
	v_cvt_f32_f16_e32 v172, v173
	v_cvt_f32_f16_sdwa v173, v173 dst_sel:DWORD dst_unused:UNUSED_PAD src0_sel:WORD_1
	global_store_dwordx4 v[182:183], v[174:177], off offset:512
	v_pk_mul_f32 v[162:163], v[150:151], v[162:163]
	v_pk_mul_f32 v[172:173], v[152:153], v[172:173]
	s_nop 0
	v_pk_fma_f32 v[174:175], v[40:41], v[140:141], v[172:173]
	v_pk_fma_f32 v[172:173], v[38:39], v[138:139], v[162:163]
	s_waitcnt vmcnt(6)
	v_cvt_f32_f16_e32 v162, v170
	v_cvt_f32_f16_sdwa v163, v170 dst_sel:DWORD dst_unused:UNUSED_PAD src0_sel:WORD_1
	v_cvt_f32_f16_e32 v170, v171
	v_cvt_f32_f16_sdwa v171, v171 dst_sel:DWORD dst_unused:UNUSED_PAD src0_sel:WORD_1
	global_store_dwordx4 v[182:183], v[172:175], off offset:576
	v_pk_mul_f32 v[162:163], v[154:155], v[162:163]
	v_pk_mul_f32 v[170:171], v[156:157], v[170:171]
	s_nop 0
	v_pk_fma_f32 v[172:173], v[44:45], v[136:137], v[170:171]
	v_pk_fma_f32 v[170:171], v[42:43], v[134:135], v[162:163]
	s_waitcnt vmcnt(6)
	v_cvt_f32_f16_e32 v162, v168
	v_cvt_f32_f16_sdwa v163, v168 dst_sel:DWORD dst_unused:UNUSED_PAD src0_sel:WORD_1
	v_cvt_f32_f16_e32 v168, v169
	v_cvt_f32_f16_sdwa v169, v169 dst_sel:DWORD dst_unused:UNUSED_PAD src0_sel:WORD_1
	global_store_dwordx4 v[182:183], v[170:173], off offset:640
	v_pk_mul_f32 v[162:163], v[160:161], v[162:163]
	v_pk_mul_f32 v[168:169], v[164:165], v[168:169]
	s_nop 0
	v_pk_fma_f32 v[170:171], v[48:49], v[132:133], v[168:169]
	v_pk_fma_f32 v[168:169], v[46:47], v[130:131], v[162:163]
	global_store_dwordx4 v[182:183], v[168:171], off offset:704
	v_lshl_add_u64 v[162:163], v[166:167], 0, v[196:197]
	global_load_dwordx2 v[168:169], v[162:163], off
	global_load_dwordx2 v[170:171], v[162:163], off offset:32
	global_load_dwordx2 v[172:173], v[162:163], off offset:64
	s_nop 0
	global_load_dwordx2 v[162:163], v[162:163], off offset:96
	v_lshl_add_u64 v[166:167], v[166:167], 0, v[198:199]
	global_load_dwordx2 v[174:175], v[166:167], off
	global_load_dwordx2 v[176:177], v[166:167], off offset:32
	global_load_dwordx2 v[178:179], v[166:167], off offset:64
	global_load_dwordx2 v[180:181], v[166:167], off offset:96
	s_waitcnt vmcnt(7)
	v_cvt_f32_f16_e32 v166, v168
	v_cvt_f32_f16_sdwa v167, v168 dst_sel:DWORD dst_unused:UNUSED_PAD src0_sel:WORD_1
	v_cvt_f32_f16_e32 v168, v169
	v_cvt_f32_f16_sdwa v169, v169 dst_sel:DWORD dst_unused:UNUSED_PAD src0_sel:WORD_1
	v_pk_mul_f32 v[166:167], v[146:147], v[166:167]
	s_nop 0
	v_pk_fma_f32 v[166:167], v[18:19], v[142:143], v[166:167]
	v_pk_mul_f32 v[168:169], v[148:149], v[168:169]
	s_nop 0
	v_pk_fma_f32 v[168:169], v[20:21], v[144:145], v[168:169]
	global_store_dwordx4 v[190:191], v[166:169], off offset:512
	s_waitcnt vmcnt(7)
	s_nop 0
	v_cvt_f32_f16_e32 v166, v170
	v_cvt_f32_f16_sdwa v167, v170 dst_sel:DWORD dst_unused:UNUSED_PAD src0_sel:WORD_1
	v_cvt_f32_f16_e32 v168, v171
	v_cvt_f32_f16_sdwa v169, v171 dst_sel:DWORD dst_unused:UNUSED_PAD src0_sel:WORD_1
	v_pk_mul_f32 v[166:167], v[150:151], v[166:167]
	s_nop 0
	v_pk_fma_f32 v[166:167], v[22:23], v[138:139], v[166:167]
	v_pk_mul_f32 v[168:169], v[152:153], v[168:169]
	s_nop 0
	v_pk_fma_f32 v[168:169], v[24:25], v[140:141], v[168:169]
	global_store_dwordx4 v[190:191], v[166:169], off offset:576
	s_waitcnt vmcnt(7)
; DI float hlo(unsigned u) { const h2_t v = __builtin_bit_cast(h2_t, u); return (float)v[0]; }
; DI float hhi(unsigned u) { const h2_t v = __builtin_bit_cast(h2_t, u); return (float)v[1]; }
; template <bool HN, bool L0>
; DI void phaseC_epi(const Params& p, f32x4 (&acc)[2][2][4][2], int l, int n0, int m0) {
;     ...
;       for (int n = 0; n < 2; ++n)
; #pragma unroll
;         for (int m = 0; m < 4; ++m) {
;           if (L0) xv[n][m] = *(const f32x4*)(xin0 + (size_t)(tok[gp * 2 + n] - rowoff) * DM + f0 + m * 16);
;           else xb[n][m] = *(const u32x2*)(p.xg + (size_t)tok[gp * 2 + n] * DM + f0 + m * 16);
;         }
; #pragma unroll
;       for (int n = 0; n < 2; ++n) {
;         const int g = gp * 2 + n;
;         float ss = 0.f;
; #pragma unroll
;         for (int m = 0; m < 4; ++m) {
;           f32x4 xx;
;           if (L0) xx = xv[n][m];
;           else {
;             xx[0] = hlo(xb[n][m][0]) * rgs[m][0]; xx[1] = hhi(xb[n][m][0]) * rgs[m][1];
;             xx[2] = hlo(xb[n][m][1]) * rgs[m][2]; xx[3] = hhi(xb[n][m][1]) * rgs[m][3];
;           }
;           f32x4 nv;
; #pragma unroll
;           for (int j = 0; j < 4; ++j) { nv[j] = xx[j] + acc[ai][gp][m][n][j]; ss += nv[j] * nv[j]; }
;           if (HN) {
;             u32x2 o;
;             o[0] = pkh2(nv[0] * gs[m][0], nv[1] * gs[m][1]);
;             o[1] = pkh2(nv[2] * gs[m][2], nv[3] * gs[m][3]);
;             *(u32x2*)(p.xg + (size_t)tok[g] * DM + f0 + m * 16) = o;
;           } else {
;             *(f32x4*)(p.out + (size_t)tok[g] * DM + f0 + m * 16) = nv;
;           }
	s_nop 0
	v_cvt_f32_f16_e32 v166, v172
	v_cvt_f32_f16_sdwa v167, v172 dst_sel:DWORD dst_unused:UNUSED_PAD src0_sel:WORD_1
	v_cvt_f32_f16_e32 v168, v173
	v_cvt_f32_f16_sdwa v169, v173 dst_sel:DWORD dst_unused:UNUSED_PAD src0_sel:WORD_1
	v_pk_mul_f32 v[166:167], v[154:155], v[166:167]
	s_nop 0
	v_pk_fma_f32 v[166:167], v[26:27], v[134:135], v[166:167]
	v_pk_mul_f32 v[168:169], v[156:157], v[168:169]
	s_nop 0
	v_pk_fma_f32 v[168:169], v[28:29], v[136:137], v[168:169]
	global_store_dwordx4 v[190:191], v[166:169], off offset:640
	s_waitcnt vmcnt(7)
	s_nop 0
	v_cvt_f32_f16_e32 v166, v162
	v_cvt_f32_f16_sdwa v167, v162 dst_sel:DWORD dst_unused:UNUSED_PAD src0_sel:WORD_1
	v_cvt_f32_f16_e32 v162, v163
	v_cvt_f32_f16_sdwa v163, v163 dst_sel:DWORD dst_unused:UNUSED_PAD src0_sel:WORD_1
	v_pk_mul_f32 v[166:167], v[160:161], v[166:167]
	s_nop 0
	v_pk_fma_f32 v[166:167], v[30:31], v[130:131], v[166:167]
	v_pk_mul_f32 v[162:163], v[164:165], v[162:163]
	s_nop 0
	v_pk_fma_f32 v[168:169], v[32:33], v[132:133], v[162:163]
	global_store_dwordx4 v[190:191], v[166:169], off offset:704
	s_waitcnt vmcnt(7)
	v_cvt_f32_f16_e32 v162, v174
	v_cvt_f32_f16_sdwa v163, v174 dst_sel:DWORD dst_unused:UNUSED_PAD src0_sel:WORD_1
	v_cvt_f32_f16_e32 v166, v175
	v_cvt_f32_f16_sdwa v167, v175 dst_sel:DWORD dst_unused:UNUSED_PAD src0_sel:WORD_1
	v_pk_mul_f32 v[146:147], v[146:147], v[162:163]
	s_nop 0
	v_pk_fma_f32 v[142:143], v[2:3], v[142:143], v[146:147]
	v_pk_mul_f32 v[148:149], v[148:149], v[166:167]
	s_nop 0
	v_pk_fma_f32 v[144:145], v[4:5], v[144:145], v[148:149]
	global_store_dwordx4 v[158:159], v[142:145], off offset:512
	s_waitcnt vmcnt(7)
	s_nop 0
	v_cvt_f32_f16_e32 v142, v176
	v_cvt_f32_f16_sdwa v143, v176 dst_sel:DWORD dst_unused:UNUSED_PAD src0_sel:WORD_1
	v_cvt_f32_f16_e32 v144, v177
	v_cvt_f32_f16_sdwa v145, v177 dst_sel:DWORD dst_unused:UNUSED_PAD src0_sel:WORD_1
	v_pk_mul_f32 v[142:143], v[150:151], v[142:143]
	s_nop 0
	v_pk_fma_f32 v[138:139], v[10:11], v[138:139], v[142:143]
	v_pk_mul_f32 v[144:145], v[152:153], v[144:145]
	s_nop 0
	v_pk_fma_f32 v[140:141], v[12:13], v[140:141], v[144:145]
	global_store_dwordx4 v[158:159], v[138:141], off offset:576
	s_waitcnt vmcnt(7)
	s_nop 0
	v_cvt_f32_f16_e32 v138, v178
	v_cvt_f32_f16_sdwa v139, v178 dst_sel:DWORD dst_unused:UNUSED_PAD src0_sel:WORD_1
	v_cvt_f32_f16_e32 v140, v179
	v_cvt_f32_f16_sdwa v141, v179 dst_sel:DWORD dst_unused:UNUSED_PAD src0_sel:WORD_1
	v_pk_mul_f32 v[138:139], v[154:155], v[138:139]
	s_nop 0
	v_pk_fma_f32 v[134:135], v[6:7], v[134:135], v[138:139]
	v_pk_mul_f32 v[140:141], v[156:157], v[140:141]
	s_nop 0
	v_pk_fma_f32 v[136:137], v[8:9], v[136:137], v[140:141]
	global_store_dwordx4 v[158:159], v[134:137], off offset:640
	s_waitcnt vmcnt(7)
	s_nop 0
	v_cvt_f32_f16_e32 v134, v180
	v_cvt_f32_f16_sdwa v135, v180 dst_sel:DWORD dst_unused:UNUSED_PAD src0_sel:WORD_1
	v_cvt_f32_f16_e32 v136, v181
	v_cvt_f32_f16_sdwa v137, v181 dst_sel:DWORD dst_unused:UNUSED_PAD src0_sel:WORD_1
	v_pk_mul_f32 v[134:135], v[160:161], v[134:135]
	s_nop 0
	v_pk_fma_f32 v[130:131], v[14:15], v[130:131], v[134:135]
	v_pk_mul_f32 v[136:137], v[164:165], v[136:137]
	s_nop 0
	v_pk_fma_f32 v[132:133], v[16:17], v[132:133], v[136:137]
	global_store_dwordx4 v[158:159], v[130:133], off offset:704
